# non-temporal (nt) stores for the in-projection and gate_up epilogue outputs
# baseline (speedup 1.0000x reference)
; __device__ __forceinline__ u32x4 pack8(const f32x4 a, const f32x4 b) { u32x4 w; w.x = cvt_pk_bf16(a[0], a[1]); w.y = cvt_pk_bf16(a[2], a[3]); w.z = cvt_pk_bf16(b[0], b[1]); w.w = cvt_pk_bf16(b[2], b[3]); return w; }
;     __device__ __forceinline__ void operator()(const f32x4 (&acc)[2][2][4][2], const Unit& u, int wr, int wc, int fr, int fq) const {
;     ...
;                 for (int m = 0; m < 4; ++m) { const int row = row0 + ai * HALF + m * 16;
;                     const int pidx = row < 16384 ? 16 + (row & 2047) : row < 16512 ? ((row - 16384) & 15) : row < 17536 ? 2064 + ((row - 16512) & 7) : 0;
;                     const f32x4* tp = (const f32x4*)(tab + ((size_t)pidx * 64 + dl) * 2);
;                     const f32x4 t0 = tp[0], t1 = tp[1], t2 = tp[2], t3 = tp[3];
;                     const f32x4 c0 = {t0.x, t0.z, t1.x, t1.z}, s0 = {t0.y, t0.w, t1.y, t1.w}, c1 = {t2.x, t2.z, t3.x, t3.z}, s1 = {t2.y, t2.w, t3.y, t3.w};
;                     const f32x4 a0 = acc[ai][0][m][0], a1 = acc[ai][0][m][1], b0 = acc[ai][1][m][0], b1 = acc[ai][1][m][1];
;                     const f32x4 o10 = (a0 * c0 - b0 * s0) * ksc, o11 = (a1 * c1 - b1 * s1) * ksc, o20 = (a0 * s0 + b0 * c0) * ksc, o21 = (a1 * s1 + b1 * c1) * ksc;
;                     bf16_t* rowp = base + (size_t)row * 1024;
;                     *(u32x4*)rowp = pack8(o10, o11); *(u32x4*)(rowp + 64) = pack8(o20, o21);
;                     if (m & 1) asm volatile("" ::: "memory"); }
.LBB0_141:
	s_movk_i32 s0, 0x3fff
	v_cmp_lt_i32_e32 vcc, s0, v144
	s_and_saveexec_b64 s[0:1], vcc
	s_xor_b64 s[16:17], exec, s[0:1]
	s_cmpk_lt_u32 s9, 0x4080
	s_cselect_b64 vcc, -1, 0
	s_cmpk_lt_u32 s9, 0x4480
	s_cselect_b64 s[0:1], -1, 0
	v_cndmask_b32_e64 v145, 0, v160, s[0:1]
	v_cndmask_b32_e32 v150, v145, v158, vcc
	s_andn2_saveexec_b64 s[0:1], s[16:17]
	s_movk_i32 s11, 0x7cf
	v_and_or_b32 v150, v144, s11, 16
	s_or_b64 exec, exec, s[0:1]
	v_mov_b32_e32 v151, v189
	v_lshlrev_b64 v[150:151], 9, v[150:151]
	v_lshl_add_u64 v[166:167], v[138:139], 0, v[150:151]
	global_load_dwordx4 v[150:153], v[166:167], off offset:48
	global_load_dwordx4 v[154:157], v[166:167], off offset:32
	global_load_dwordx4 v[162:165], v[166:167], off offset:16
	s_nop 0
	global_load_dwordx4 v[166:169], v[166:167], off
	s_lshl_b32 s0, s37, 1
	s_and_b32 s0, s0, 6
	s_or_b32 s0, s0, s34
	s_cmp_gt_i32 s37, 3
	s_cselect_b64 vcc, -1, 0
	s_ashr_i32 s1, s37, 2
	s_mul_hi_i32 s11, s1, 0x2280000
	s_mul_i32 s1, s1, 0x2280000
	v_readlane_b32 s16, v254, 19
	s_add_u32 s1, s16, s1
	v_readlane_b32 s16, v254, 20
	s_addc_u32 s11, s16, s11
	s_lshl_b32 s0, s0, 8
	v_mov_b32_e32 v145, 0x3db504f3
	s_add_u32 s0, s1, s0
	v_cndmask_b32_e32 v146, 1.0, v145, vcc
	s_addc_u32 s1, s11, 0
	v_ashrrev_i32_e32 v145, 31, v144
	v_lshl_add_u64 v[148:149], s[0:1], 0, v[188:189]
	s_movk_i32 s0, 0x3fff
	s_waitcnt vmcnt(0)
	v_mov_b32_e32 v178, v155
	v_mov_b32_e32 v170, v163
	v_mov_b32_e32 v171, v165
	v_pk_mul_f32 v[172:173], v[118:119], v[170:171]
	v_mov_b32_e32 v174, v167
	v_mov_b32_e32 v175, v169
	v_mov_b32_e32 v163, v164
	v_mov_b32_e32 v179, v157
	v_mov_b32_e32 v155, v156
	v_pk_mul_f32 v[176:177], v[116:117], v[174:175]
	v_mov_b32_e32 v167, v168
	v_pk_fma_f32 v[164:165], v[126:127], v[162:163], v[172:173] neg_lo:[0,0,1] neg_hi:[0,0,1]
	v_mov_b32_e32 v172, v151
	v_mov_b32_e32 v173, v153
	v_pk_mul_f32 v[180:181], v[112:113], v[178:179]
	v_mov_b32_e32 v151, v152
	v_pk_mul_f32 v[112:113], v[112:113], v[154:155]
	v_pk_fma_f32 v[168:169], v[124:125], v[166:167], v[176:177] neg_lo:[0,0,1] neg_hi:[0,0,1]
	v_pk_mul_f32 v[176:177], v[114:115], v[172:173]
	v_pk_mul_f32 v[114:115], v[114:115], v[150:151]
	v_pk_fma_f32 v[112:113], v[120:121], v[178:179], v[112:113]
	v_pk_fma_f32 v[152:153], v[122:123], v[150:151], v[176:177] neg_lo:[0,0,1] neg_hi:[0,0,1]
	v_pk_mul_f32 v[116:117], v[116:117], v[166:167]
	v_pk_fma_f32 v[114:115], v[122:123], v[172:173], v[114:115]
	v_pk_mul_f32 v[122:123], v[146:147], v[112:113] op_sel_hi:[0,1]
	v_lshlrev_b64 v[112:113], 11, v[144:145]
	v_pk_mul_f32 v[168:169], v[146:147], v[168:169] op_sel_hi:[0,1]
	v_pk_fma_f32 v[156:157], v[120:121], v[154:155], v[180:181] neg_lo:[0,0,1] neg_hi:[0,0,1]
	v_pk_mul_f32 v[118:119], v[118:119], v[162:163]
	v_pk_fma_f32 v[116:117], v[124:125], v[174:175], v[116:117]
	v_lshl_add_u64 v[124:125], v[148:149], 0, v[112:113]
	v_cvt_pk_bf16_f32 v112, v168, v169
	v_pk_mul_f32 v[164:165], v[146:147], v[164:165] op_sel_hi:[0,1]
	v_pk_mul_f32 v[152:153], v[146:147], v[152:153] op_sel_hi:[0,1]
	v_pk_mul_f32 v[156:157], v[146:147], v[156:157] op_sel_hi:[0,1]
	v_pk_fma_f32 v[118:119], v[126:127], v[170:171], v[118:119]
	v_pk_mul_f32 v[116:117], v[146:147], v[116:117] op_sel_hi:[0,1]
	v_pk_mul_f32 v[120:121], v[146:147], v[114:115] op_sel_hi:[0,1]
	v_cvt_pk_bf16_f32 v113, v164, v165
	v_cvt_pk_bf16_f32 v114, v156, v157
	v_cvt_pk_bf16_f32 v115, v152, v153
	global_store_dwordx4 v[124:125], v[112:115], off nt
	v_pk_mul_f32 v[118:119], v[146:147], v[118:119] op_sel_hi:[0,1]
	s_nop 0
	v_cvt_pk_bf16_f32 v112, v116, v117
	v_cvt_pk_bf16_f32 v113, v118, v119
	v_cvt_pk_bf16_f32 v114, v122, v123
	v_cvt_pk_bf16_f32 v115, v120, v121
	global_store_dwordx4 v[124:125], v[112:115], off offset:128 nt
	s_nop 1
	v_or_b32_e32 v112, 16, v144
	v_cmp_lt_i32_e32 vcc, s0, v112
	s_and_saveexec_b64 s[0:1], vcc
	s_xor_b64 s[16:17], exec, s[0:1]
	s_cmpk_lt_u32 s9, 0x4080
	s_cselect_b64 vcc, -1, 0
	s_cmpk_lt_u32 s9, 0x4480
	s_cselect_b64 s[0:1], -1, 0
	v_cndmask_b32_e64 v113, 0, v160, s[0:1]
	v_cndmask_b32_e32 v114, v113, v158, vcc
	s_andn2_saveexec_b64 s[0:1], s[16:17]
	v_and_b32_e32 v113, 0x7df, v112
	v_add_u32_e32 v114, 16, v113
	s_or_b64 exec, exec, s[0:1]
	v_mov_b32_e32 v115, v189
	v_lshlrev_b64 v[114:115], 9, v[114:115]
	v_lshl_add_u64 v[114:115], v[138:139], 0, v[114:115]
	global_load_dwordx4 v[122:125], v[114:115], off offset:48
	global_load_dwordx4 v[150:153], v[114:115], off offset:32
	global_load_dwordx4 v[154:157], v[114:115], off offset:16
	global_load_dwordx4 v[162:165], v[114:115], off
	v_mov_b32_e32 v147, v146
	v_ashrrev_i32_e32 v113, 31, v112
	s_movk_i32 s0, 0x3fff
	s_waitcnt vmcnt(2)
	v_mov_b32_e32 v168, v151
	v_mov_b32_e32 v169, v153
	v_mov_b32_e32 v151, v152
	s_waitcnt vmcnt(1)
	v_mov_b32_e32 v126, v155
	v_mov_b32_e32 v127, v157
	s_waitcnt vmcnt(0)
; __device__ __forceinline__ u32x4 pack8(const f32x4 a, const f32x4 b) { u32x4 w; w.x = cvt_pk_bf16(a[0], a[1]); w.y = cvt_pk_bf16(a[2], a[3]); w.z = cvt_pk_bf16(b[0], b[1]); w.w = cvt_pk_bf16(b[2], b[3]); return w; }
;     __device__ __forceinline__ void operator()(const f32x4 (&acc)[2][2][4][2], const Unit& u, int wr, int wc, int fr, int fq) const {
;     ...
;                 for (int m = 0; m < 4; ++m) { const int row = row0 + ai * HALF + m * 16;
;                     const int pidx = row < 16384 ? 16 + (row & 2047) : row < 16512 ? ((row - 16384) & 15) : row < 17536 ? 2064 + ((row - 16512) & 7) : 0;
;                     const f32x4* tp = (const f32x4*)(tab + ((size_t)pidx * 64 + dl) * 2);
;                     const f32x4 t0 = tp[0], t1 = tp[1], t2 = tp[2], t3 = tp[3];
;                     const f32x4 c0 = {t0.x, t0.z, t1.x, t1.z}, s0 = {t0.y, t0.w, t1.y, t1.w}, c1 = {t2.x, t2.z, t3.x, t3.z}, s1 = {t2.y, t2.w, t3.y, t3.w};
;                     const f32x4 a0 = acc[ai][0][m][0], a1 = acc[ai][0][m][1], b0 = acc[ai][1][m][0], b1 = acc[ai][1][m][1];
;                     const f32x4 o10 = (a0 * c0 - b0 * s0) * ksc, o11 = (a1 * c1 - b1 * s1) * ksc, o20 = (a0 * s0 + b0 * c0) * ksc, o21 = (a1 * s1 + b1 * c1) * ksc;
;                     bf16_t* rowp = base + (size_t)row * 1024;
;                     *(u32x4*)rowp = pack8(o10, o11); *(u32x4*)(rowp + 64) = pack8(o20, o21);
;                     if (m & 1) asm volatile("" ::: "memory"); }
	v_mov_b32_e32 v166, v163
	v_mov_b32_e32 v167, v165
	v_mov_b32_e32 v163, v164
	v_mov_b32_e32 v164, v123
	v_mov_b32_e32 v165, v125
	v_pk_mul_f32 v[120:121], v[96:97], v[168:169]
	v_mov_b32_e32 v123, v124
	v_pk_mul_f32 v[96:97], v[96:97], v[150:151]
	v_pk_mul_f32 v[114:115], v[102:103], v[126:127]
	v_pk_mul_f32 v[116:117], v[100:101], v[166:167]
	v_mov_b32_e32 v155, v156
	v_pk_mul_f32 v[118:119], v[98:99], v[164:165]
	v_pk_fma_f32 v[120:121], v[104:105], v[150:151], v[120:121] neg_lo:[0,0,1] neg_hi:[0,0,1]
	v_pk_mul_f32 v[100:101], v[100:101], v[162:163]
	v_pk_mul_f32 v[98:99], v[98:99], v[122:123]
	v_pk_fma_f32 v[104:105], v[104:105], v[168:169], v[96:97]
	v_pk_fma_f32 v[116:117], v[108:109], v[162:163], v[116:117] neg_lo:[0,0,1] neg_hi:[0,0,1]
	v_pk_fma_f32 v[114:115], v[110:111], v[154:155], v[114:115] neg_lo:[0,0,1] neg_hi:[0,0,1]
	v_mov_b32_e32 v156, v146
	v_mov_b32_e32 v157, v146
	v_pk_mul_f32 v[102:103], v[102:103], v[154:155]
	v_pk_fma_f32 v[108:109], v[108:109], v[166:167], v[100:101]
	v_pk_fma_f32 v[96:97], v[106:107], v[164:165], v[98:99]
	v_pk_mul_f32 v[98:99], v[146:147], v[104:105]
	v_lshlrev_b64 v[104:105], 11, v[112:113]
	v_pk_mul_f32 v[114:115], v[156:157], v[114:115]
	v_pk_mul_f32 v[116:117], v[146:147], v[116:117]
	v_pk_fma_f32 v[118:119], v[106:107], v[122:123], v[118:119] neg_lo:[0,0,1] neg_hi:[0,0,1]
	v_pk_fma_f32 v[100:101], v[110:111], v[126:127], v[102:103]
	v_pk_mul_f32 v[102:103], v[146:147], v[108:109]
	v_lshl_add_u64 v[108:109], v[148:149], 0, v[104:105]
	v_cvt_pk_bf16_f32 v104, v116, v117
	v_cvt_pk_bf16_f32 v105, v114, v115
	v_pk_mul_f32 v[118:119], v[156:157], v[118:119]
	v_pk_mul_f32 v[120:121], v[146:147], v[120:121]
	v_pk_mul_f32 v[100:101], v[156:157], v[100:101]
	v_pk_mul_f32 v[96:97], v[156:157], v[96:97]
	v_cvt_pk_bf16_f32 v106, v120, v121
	v_cvt_pk_bf16_f32 v107, v118, v119
	global_store_dwordx4 v[108:109], v[104:107], off nt
	v_cvt_pk_bf16_f32 v102, v102, v103
	v_cvt_pk_bf16_f32 v103, v100, v101
	s_nop 1
	v_cvt_pk_bf16_f32 v104, v98, v99
	v_cvt_pk_bf16_f32 v105, v96, v97
	global_store_dwordx4 v[108:109], v[102:105], off offset:128 nt
	v_or_b32_e32 v96, 32, v144
	v_cmp_lt_i32_e32 vcc, s0, v96
	s_and_saveexec_b64 s[0:1], vcc
	s_xor_b64 s[16:17], exec, s[0:1]
	s_cmpk_lt_u32 s9, 0x4080
	s_cselect_b64 vcc, -1, 0
	s_cmpk_lt_u32 s9, 0x4480
	s_cselect_b64 s[0:1], -1, 0
	v_cndmask_b32_e64 v97, 0, v160, s[0:1]
	v_cndmask_b32_e32 v98, v97, v158, vcc
	s_andn2_saveexec_b64 s[0:1], s[16:17]
	s_movk_i32 s11, 0x7ef
	v_and_or_b32 v98, v96, s11, 16
	s_or_b64 exec, exec, s[0:1]
	v_mov_b32_e32 v99, v189
	v_lshlrev_b64 v[98:99], 9, v[98:99]
	v_lshl_add_u64 v[110:111], v[138:139], 0, v[98:99]
	global_load_dwordx4 v[98:101], v[110:111], off offset:48
	global_load_dwordx4 v[102:105], v[110:111], off offset:32
	global_load_dwordx4 v[106:109], v[110:111], off offset:16
	s_nop 0
	global_load_dwordx4 v[110:113], v[110:111], off
	v_ashrrev_i32_e32 v97, 31, v96
	s_movk_i32 s0, 0x3fff
	s_waitcnt vmcnt(2)
	v_mov_b32_e32 v124, v103
	v_mov_b32_e32 v125, v105
	s_waitcnt vmcnt(0)
	v_mov_b32_e32 v118, v111
	v_mov_b32_e32 v119, v113
	v_pk_mul_f32 v[120:121], v[84:85], v[118:119]
	v_mov_b32_e32 v111, v112
	v_mov_b32_e32 v103, v104
	v_pk_fma_f32 v[112:113], v[92:93], v[110:111], v[120:121] neg_lo:[0,0,1] neg_hi:[0,0,1]
	v_mov_b32_e32 v120, v99
	v_mov_b32_e32 v121, v101
	v_pk_mul_f32 v[126:127], v[80:81], v[124:125]
	v_mov_b32_e32 v99, v100
	v_pk_mul_f32 v[80:81], v[80:81], v[102:103]
	v_mov_b32_e32 v114, v107
	v_mov_b32_e32 v115, v109
	v_pk_mul_f32 v[122:123], v[82:83], v[120:121]
	v_pk_mul_f32 v[82:83], v[82:83], v[98:99]
	v_pk_fma_f32 v[80:81], v[88:89], v[124:125], v[80:81]
	v_pk_mul_f32 v[116:117], v[86:87], v[114:115]
	v_mov_b32_e32 v107, v108
	v_pk_fma_f32 v[100:101], v[90:91], v[98:99], v[122:123] neg_lo:[0,0,1] neg_hi:[0,0,1]
	v_pk_mul_f32 v[84:85], v[84:85], v[110:111]
	v_pk_fma_f32 v[82:83], v[90:91], v[120:121], v[82:83]
	v_pk_mul_f32 v[90:91], v[146:147], v[80:81]
	v_lshlrev_b64 v[80:81], 11, v[96:97]
	v_pk_fma_f32 v[108:109], v[94:95], v[106:107], v[116:117] neg_lo:[0,0,1] neg_hi:[0,0,1]
	v_mov_b32_e32 v116, v146
	v_mov_b32_e32 v117, v146
	v_pk_mul_f32 v[112:113], v[146:147], v[112:113]
	v_pk_fma_f32 v[104:105], v[88:89], v[102:103], v[126:127] neg_lo:[0,0,1] neg_hi:[0,0,1]
	v_pk_mul_f32 v[86:87], v[86:87], v[106:107]
	v_pk_fma_f32 v[84:85], v[92:93], v[118:119], v[84:85]
	v_lshl_add_u64 v[92:93], v[148:149], 0, v[80:81]
	v_cvt_pk_bf16_f32 v80, v112, v113
	v_pk_mul_f32 v[108:109], v[116:117], v[108:109]
	v_pk_mul_f32 v[100:101], v[116:117], v[100:101]
	v_pk_mul_f32 v[104:105], v[146:147], v[104:105]
	v_pk_fma_f32 v[86:87], v[94:95], v[114:115], v[86:87]
	v_pk_mul_f32 v[84:85], v[146:147], v[84:85]
	v_pk_mul_f32 v[88:89], v[116:117], v[82:83]
	v_cvt_pk_bf16_f32 v81, v108, v109
	v_cvt_pk_bf16_f32 v82, v104, v105
	v_cvt_pk_bf16_f32 v83, v100, v101
	global_store_dwordx4 v[92:93], v[80:83], off nt
	v_pk_mul_f32 v[86:87], v[116:117], v[86:87]
	s_nop 0
	v_cvt_pk_bf16_f32 v80, v84, v85
	v_cvt_pk_bf16_f32 v81, v86, v87
	v_cvt_pk_bf16_f32 v82, v90, v91
	v_cvt_pk_bf16_f32 v83, v88, v89
	global_store_dwordx4 v[92:93], v[80:83], off offset:128 nt
	s_nop 1
	v_or_b32_e32 v80, 48, v144
	v_cmp_lt_i32_e32 vcc, s0, v80
	s_and_saveexec_b64 s[0:1], vcc
	s_xor_b64 s[16:17], exec, s[0:1]
	s_cmpk_lt_u32 s9, 0x4080
	s_cselect_b64 vcc, -1, 0
	s_cmpk_lt_u32 s9, 0x4480
	s_cselect_b64 s[0:1], -1, 0
	v_cndmask_b32_e64 v81, 0, v160, s[0:1]
	v_cndmask_b32_e32 v82, v81, v158, vcc
	s_andn2_saveexec_b64 s[0:1], s[16:17]
	v_and_b32_e32 v81, 0x7ff, v80
	v_add_u32_e32 v82, 16, v81
	s_or_b64 exec, exec, s[0:1]
	v_mov_b32_e32 v83, v189
	v_lshlrev_b64 v[82:83], 9, v[82:83]
	v_lshl_add_u64 v[82:83], v[138:139], 0, v[82:83]
	global_load_dwordx4 v[90:93], v[82:83], off offset:48
	global_load_dwordx4 v[94:97], v[82:83], off offset:32
	global_load_dwordx4 v[98:101], v[82:83], off offset:16
	global_load_dwordx4 v[102:105], v[82:83], off
	v_ashrrev_i32_e32 v81, 31, v80
	s_movk_i32 s0, 0x3f7f
	v_cmp_lt_i32_e32 vcc, s0, v144
	s_waitcnt vmcnt(2)
; __device__ __forceinline__ u32x4 pack8(const f32x4 a, const f32x4 b) { u32x4 w; w.x = cvt_pk_bf16(a[0], a[1]); w.y = cvt_pk_bf16(a[2], a[3]); w.z = cvt_pk_bf16(b[0], b[1]); w.w = cvt_pk_bf16(b[2], b[3]); return w; }
;     __device__ __forceinline__ void operator()(const f32x4 (&acc)[2][2][4][2], const Unit& u, int wr, int wc, int fr, int fq) const {
;     ...
;                 for (int m = 0; m < 4; ++m) { const int row = row0 + ai * HALF + m * 16;
;                     const int pidx = row < 16384 ? 16 + (row & 2047) : row < 16512 ? ((row - 16384) & 15) : row < 17536 ? 2064 + ((row - 16512) & 7) : 0;
;                     const f32x4* tp = (const f32x4*)(tab + ((size_t)pidx * 64 + dl) * 2);
;                     const f32x4 t0 = tp[0], t1 = tp[1], t2 = tp[2], t3 = tp[3];
;                     const f32x4 c0 = {t0.x, t0.z, t1.x, t1.z}, s0 = {t0.y, t0.w, t1.y, t1.w}, c1 = {t2.x, t2.z, t3.x, t3.z}, s1 = {t2.y, t2.w, t3.y, t3.w};
;                     const f32x4 a0 = acc[ai][0][m][0], a1 = acc[ai][0][m][1], b0 = acc[ai][1][m][0], b1 = acc[ai][1][m][1];
;                     const f32x4 o10 = (a0 * c0 - b0 * s0) * ksc, o11 = (a1 * c1 - b1 * s1) * ksc, o20 = (a0 * s0 + b0 * c0) * ksc, o21 = (a1 * s1 + b1 * c1) * ksc;
;                     bf16_t* rowp = base + (size_t)row * 1024;
;                     *(u32x4*)rowp = pack8(o10, o11); *(u32x4*)(rowp + 64) = pack8(o20, o21);
;                     if (m & 1) asm volatile("" ::: "memory"); }
	v_mov_b32_e32 v110, v95
	v_mov_b32_e32 v111, v97
	v_mov_b32_e32 v95, v96
	s_waitcnt vmcnt(1)
	v_mov_b32_e32 v106, v99
	v_mov_b32_e32 v107, v101
	s_waitcnt vmcnt(0)
	v_mov_b32_e32 v108, v103
	v_mov_b32_e32 v109, v105
	v_mov_b32_e32 v103, v104
	v_mov_b32_e32 v104, v91
	v_mov_b32_e32 v105, v93
	v_pk_mul_f32 v[88:89], v[64:65], v[110:111]
	v_mov_b32_e32 v91, v92
	v_pk_mul_f32 v[64:65], v[64:65], v[94:95]
	v_pk_mul_f32 v[82:83], v[70:71], v[106:107]
	v_pk_mul_f32 v[84:85], v[68:69], v[108:109]
	v_mov_b32_e32 v99, v100
	v_pk_mul_f32 v[86:87], v[66:67], v[104:105]
	v_pk_fma_f32 v[88:89], v[72:73], v[94:95], v[88:89] neg_lo:[0,0,1] neg_hi:[0,0,1]
	v_pk_mul_f32 v[68:69], v[68:69], v[102:103]
	v_pk_mul_f32 v[66:67], v[66:67], v[90:91]
	v_pk_fma_f32 v[72:73], v[72:73], v[110:111], v[64:65]
	v_pk_fma_f32 v[84:85], v[76:77], v[102:103], v[84:85] neg_lo:[0,0,1] neg_hi:[0,0,1]
	v_pk_fma_f32 v[82:83], v[78:79], v[98:99], v[82:83] neg_lo:[0,0,1] neg_hi:[0,0,1]
	v_mov_b32_e32 v100, v146
	v_mov_b32_e32 v101, v146
	v_pk_mul_f32 v[70:71], v[70:71], v[98:99]
	v_pk_fma_f32 v[76:77], v[76:77], v[108:109], v[68:69]
	v_pk_fma_f32 v[64:65], v[74:75], v[104:105], v[66:67]
	v_pk_mul_f32 v[66:67], v[146:147], v[72:73]
	v_lshlrev_b64 v[72:73], 11, v[80:81]
	v_pk_mul_f32 v[82:83], v[100:101], v[82:83]
	v_pk_mul_f32 v[84:85], v[146:147], v[84:85]
	v_pk_fma_f32 v[86:87], v[74:75], v[90:91], v[86:87] neg_lo:[0,0,1] neg_hi:[0,0,1]
	v_pk_fma_f32 v[68:69], v[78:79], v[106:107], v[70:71]
	v_pk_mul_f32 v[70:71], v[146:147], v[76:77]
	v_lshl_add_u64 v[76:77], v[148:149], 0, v[72:73]
	v_cvt_pk_bf16_f32 v72, v84, v85
	v_cvt_pk_bf16_f32 v73, v82, v83
	v_pk_mul_f32 v[86:87], v[100:101], v[86:87]
	v_pk_mul_f32 v[88:89], v[146:147], v[88:89]
	v_pk_mul_f32 v[68:69], v[100:101], v[68:69]
	v_pk_mul_f32 v[64:65], v[100:101], v[64:65]
	v_cvt_pk_bf16_f32 v74, v88, v89
	v_cvt_pk_bf16_f32 v75, v86, v87
	global_store_dwordx4 v[76:77], v[72:75], off nt
	v_cvt_pk_bf16_f32 v70, v70, v71
	v_cvt_pk_bf16_f32 v71, v68, v69
	s_nop 1
	v_cvt_pk_bf16_f32 v72, v66, v67
	v_cvt_pk_bf16_f32 v73, v64, v65
	global_store_dwordx4 v[76:77], v[70:73], off offset:128 nt
	v_add_u32_e32 v64, 0x80, v144
	s_and_saveexec_b64 s[0:1], vcc
	s_xor_b64 s[0:1], exec, s[0:1]
	s_movk_i32 s9, 0x4480
	v_cmp_gt_u32_e32 vcc, s9, v64
	s_movk_i32 s9, 0x4080
	s_nop 0
	v_cndmask_b32_e32 v65, 0, v160, vcc
	v_cmp_gt_u32_e32 vcc, s9, v64
	s_nop 1
	v_cndmask_b32_e32 v66, v65, v158, vcc
	s_andn2_saveexec_b64 s[0:1], s[0:1]
	s_movk_i32 s9, 0x7cf
	v_and_or_b32 v66, v64, s9, 16
	s_or_b64 exec, exec, s[0:1]
	v_mov_b32_e32 v67, v189
	v_lshlrev_b64 v[66:67], 9, v[66:67]
	v_lshl_add_u64 v[78:79], v[138:139], 0, v[66:67]
	global_load_dwordx4 v[66:69], v[78:79], off offset:48
	global_load_dwordx4 v[70:73], v[78:79], off offset:32
	global_load_dwordx4 v[74:77], v[78:79], off offset:16
	s_nop 0
	global_load_dwordx4 v[78:81], v[78:79], off
	v_ashrrev_i32_e32 v65, 31, v64
	s_movk_i32 s0, 0x3f6f
	v_cmp_lt_i32_e32 vcc, s0, v144
	s_waitcnt vmcnt(2)
	v_mov_b32_e32 v92, v71
	v_mov_b32_e32 v93, v73
	s_waitcnt vmcnt(0)
	v_mov_b32_e32 v86, v79
	v_mov_b32_e32 v87, v81
	v_pk_mul_f32 v[88:89], v[52:53], v[86:87]
	v_mov_b32_e32 v79, v80
	v_mov_b32_e32 v71, v72
	v_pk_fma_f32 v[80:81], v[60:61], v[78:79], v[88:89] neg_lo:[0,0,1] neg_hi:[0,0,1]
	v_mov_b32_e32 v88, v67
	v_mov_b32_e32 v89, v69
	v_pk_mul_f32 v[94:95], v[48:49], v[92:93]
	v_mov_b32_e32 v67, v68
	v_pk_mul_f32 v[48:49], v[48:49], v[70:71]
	v_mov_b32_e32 v82, v75
	v_mov_b32_e32 v83, v77
	v_pk_mul_f32 v[90:91], v[50:51], v[88:89]
	v_pk_mul_f32 v[50:51], v[50:51], v[66:67]
	v_pk_fma_f32 v[48:49], v[56:57], v[92:93], v[48:49]
	v_pk_mul_f32 v[84:85], v[54:55], v[82:83]
	v_mov_b32_e32 v75, v76
	v_pk_fma_f32 v[68:69], v[58:59], v[66:67], v[90:91] neg_lo:[0,0,1] neg_hi:[0,0,1]
	v_pk_mul_f32 v[52:53], v[52:53], v[78:79]
	v_pk_fma_f32 v[50:51], v[58:59], v[88:89], v[50:51]
	v_pk_mul_f32 v[58:59], v[146:147], v[48:49]
	v_lshlrev_b64 v[48:49], 11, v[64:65]
	v_pk_fma_f32 v[76:77], v[62:63], v[74:75], v[84:85] neg_lo:[0,0,1] neg_hi:[0,0,1]
	v_mov_b32_e32 v84, v146
	v_mov_b32_e32 v85, v146
	v_pk_mul_f32 v[80:81], v[146:147], v[80:81]
	v_pk_fma_f32 v[72:73], v[56:57], v[70:71], v[94:95] neg_lo:[0,0,1] neg_hi:[0,0,1]
	v_pk_mul_f32 v[54:55], v[54:55], v[74:75]
	v_pk_fma_f32 v[52:53], v[60:61], v[86:87], v[52:53]
	v_lshl_add_u64 v[60:61], v[148:149], 0, v[48:49]
	v_cvt_pk_bf16_f32 v48, v80, v81
	v_pk_mul_f32 v[76:77], v[84:85], v[76:77]
	v_pk_mul_f32 v[68:69], v[84:85], v[68:69]
	v_pk_mul_f32 v[72:73], v[146:147], v[72:73]
	v_pk_fma_f32 v[54:55], v[62:63], v[82:83], v[54:55]
	v_pk_mul_f32 v[52:53], v[146:147], v[52:53]
	v_pk_mul_f32 v[56:57], v[84:85], v[50:51]
	v_cvt_pk_bf16_f32 v49, v76, v77
	v_cvt_pk_bf16_f32 v50, v72, v73
	v_cvt_pk_bf16_f32 v51, v68, v69
	global_store_dwordx4 v[60:61], v[48:51], off nt
	v_pk_mul_f32 v[54:55], v[84:85], v[54:55]
	s_nop 0
	v_cvt_pk_bf16_f32 v48, v52, v53
	v_cvt_pk_bf16_f32 v49, v54, v55
	v_cvt_pk_bf16_f32 v50, v58, v59
	v_cvt_pk_bf16_f32 v51, v56, v57
	global_store_dwordx4 v[60:61], v[48:51], off offset:128 nt
	s_nop 1
	v_add_u32_e32 v48, 0x90, v144
	s_and_saveexec_b64 s[0:1], vcc
	s_xor_b64 s[0:1], exec, s[0:1]
	s_movk_i32 s9, 0x4480
	v_cmp_gt_u32_e32 vcc, s9, v48
	s_movk_i32 s9, 0x4080
	s_nop 0
	v_cndmask_b32_e32 v49, 0, v160, vcc
	v_cmp_gt_u32_e32 vcc, s9, v48
	s_nop 1
	v_cndmask_b32_e32 v50, v49, v158, vcc
	s_andn2_saveexec_b64 s[0:1], s[0:1]
	v_and_b32_e32 v49, 0x7df, v48
	v_add_u32_e32 v50, 16, v49
	s_or_b64 exec, exec, s[0:1]
	v_mov_b32_e32 v51, v189
	v_lshlrev_b64 v[50:51], 9, v[50:51]
	v_lshl_add_u64 v[50:51], v[138:139], 0, v[50:51]
	global_load_dwordx4 v[58:61], v[50:51], off offset:48
	global_load_dwordx4 v[62:65], v[50:51], off offset:32
	global_load_dwordx4 v[66:69], v[50:51], off offset:16
	global_load_dwordx4 v[70:73], v[50:51], off
	v_ashrrev_i32_e32 v49, 31, v48
	s_movk_i32 s0, 0x3f5f
	v_cmp_lt_i32_e32 vcc, s0, v144
	s_waitcnt vmcnt(2)
; __device__ __forceinline__ u32x4 pack8(const f32x4 a, const f32x4 b) { u32x4 w; w.x = cvt_pk_bf16(a[0], a[1]); w.y = cvt_pk_bf16(a[2], a[3]); w.z = cvt_pk_bf16(b[0], b[1]); w.w = cvt_pk_bf16(b[2], b[3]); return w; }
;     __device__ __forceinline__ void operator()(const f32x4 (&acc)[2][2][4][2], const Unit& u, int wr, int wc, int fr, int fq) const {
;     ...
;                 for (int m = 0; m < 4; ++m) { const int row = row0 + ai * HALF + m * 16;
;                     const int pidx = row < 16384 ? 16 + (row & 2047) : row < 16512 ? ((row - 16384) & 15) : row < 17536 ? 2064 + ((row - 16512) & 7) : 0;
;                     const f32x4* tp = (const f32x4*)(tab + ((size_t)pidx * 64 + dl) * 2);
;                     const f32x4 t0 = tp[0], t1 = tp[1], t2 = tp[2], t3 = tp[3];
;                     const f32x4 c0 = {t0.x, t0.z, t1.x, t1.z}, s0 = {t0.y, t0.w, t1.y, t1.w}, c1 = {t2.x, t2.z, t3.x, t3.z}, s1 = {t2.y, t2.w, t3.y, t3.w};
;                     const f32x4 a0 = acc[ai][0][m][0], a1 = acc[ai][0][m][1], b0 = acc[ai][1][m][0], b1 = acc[ai][1][m][1];
;                     const f32x4 o10 = (a0 * c0 - b0 * s0) * ksc, o11 = (a1 * c1 - b1 * s1) * ksc, o20 = (a0 * s0 + b0 * c0) * ksc, o21 = (a1 * s1 + b1 * c1) * ksc;
;                     bf16_t* rowp = base + (size_t)row * 1024;
;                     *(u32x4*)rowp = pack8(o10, o11); *(u32x4*)(rowp + 64) = pack8(o20, o21);
;                     if (m & 1) asm volatile("" ::: "memory"); }
	v_mov_b32_e32 v78, v63
	v_mov_b32_e32 v79, v65
	v_mov_b32_e32 v63, v64
	s_waitcnt vmcnt(1)
	v_mov_b32_e32 v74, v67
	v_mov_b32_e32 v75, v69
	s_waitcnt vmcnt(0)
	v_mov_b32_e32 v76, v71
	v_mov_b32_e32 v77, v73
	v_mov_b32_e32 v71, v72
	v_mov_b32_e32 v72, v59
	v_mov_b32_e32 v73, v61
	v_pk_mul_f32 v[56:57], v[32:33], v[78:79]
	v_mov_b32_e32 v59, v60
	v_pk_mul_f32 v[32:33], v[32:33], v[62:63]
	v_pk_mul_f32 v[50:51], v[38:39], v[74:75]
	v_pk_mul_f32 v[52:53], v[36:37], v[76:77]
	v_mov_b32_e32 v67, v68
	v_pk_mul_f32 v[54:55], v[34:35], v[72:73]
	v_pk_fma_f32 v[56:57], v[40:41], v[62:63], v[56:57] neg_lo:[0,0,1] neg_hi:[0,0,1]
	v_pk_mul_f32 v[36:37], v[36:37], v[70:71]
	v_pk_mul_f32 v[34:35], v[34:35], v[58:59]
	v_pk_fma_f32 v[40:41], v[40:41], v[78:79], v[32:33]
	v_pk_fma_f32 v[52:53], v[44:45], v[70:71], v[52:53] neg_lo:[0,0,1] neg_hi:[0,0,1]
	v_pk_fma_f32 v[50:51], v[46:47], v[66:67], v[50:51] neg_lo:[0,0,1] neg_hi:[0,0,1]
	v_mov_b32_e32 v68, v146
	v_mov_b32_e32 v69, v146
	v_pk_mul_f32 v[38:39], v[38:39], v[66:67]
	v_pk_fma_f32 v[44:45], v[44:45], v[76:77], v[36:37]
	v_pk_fma_f32 v[32:33], v[42:43], v[72:73], v[34:35]
	v_pk_mul_f32 v[34:35], v[146:147], v[40:41]
	v_lshlrev_b64 v[40:41], 11, v[48:49]
	v_pk_mul_f32 v[50:51], v[68:69], v[50:51]
	v_pk_mul_f32 v[52:53], v[146:147], v[52:53]
	v_pk_fma_f32 v[54:55], v[42:43], v[58:59], v[54:55] neg_lo:[0,0,1] neg_hi:[0,0,1]
	v_pk_fma_f32 v[36:37], v[46:47], v[74:75], v[38:39]
	v_pk_mul_f32 v[38:39], v[146:147], v[44:45]
	v_lshl_add_u64 v[44:45], v[148:149], 0, v[40:41]
	v_cvt_pk_bf16_f32 v40, v52, v53
	v_cvt_pk_bf16_f32 v41, v50, v51
	v_pk_mul_f32 v[54:55], v[68:69], v[54:55]
	v_pk_mul_f32 v[56:57], v[146:147], v[56:57]
	v_pk_mul_f32 v[36:37], v[68:69], v[36:37]
	v_pk_mul_f32 v[32:33], v[68:69], v[32:33]
	v_cvt_pk_bf16_f32 v42, v56, v57
	v_cvt_pk_bf16_f32 v43, v54, v55
	global_store_dwordx4 v[44:45], v[40:43], off nt
	v_cvt_pk_bf16_f32 v38, v38, v39
	v_cvt_pk_bf16_f32 v39, v36, v37
	s_nop 1
	v_cvt_pk_bf16_f32 v40, v34, v35
	v_cvt_pk_bf16_f32 v41, v32, v33
	global_store_dwordx4 v[44:45], v[38:41], off offset:128 nt
	v_add_u32_e32 v32, 0xa0, v144
	s_and_saveexec_b64 s[0:1], vcc
	s_xor_b64 s[0:1], exec, s[0:1]
	s_movk_i32 s9, 0x4480
	v_cmp_gt_u32_e32 vcc, s9, v32
	s_movk_i32 s9, 0x4080
	s_nop 0
	v_cndmask_b32_e32 v33, 0, v160, vcc
	v_cmp_gt_u32_e32 vcc, s9, v32
	s_nop 1
	v_cndmask_b32_e32 v34, v33, v158, vcc
	s_andn2_saveexec_b64 s[0:1], s[0:1]
	s_movk_i32 s9, 0x7ef
	v_and_or_b32 v34, v32, s9, 16
	s_or_b64 exec, exec, s[0:1]
	v_mov_b32_e32 v35, v189
	v_lshlrev_b64 v[34:35], 9, v[34:35]
	v_lshl_add_u64 v[46:47], v[138:139], 0, v[34:35]
	global_load_dwordx4 v[34:37], v[46:47], off offset:48
	global_load_dwordx4 v[38:41], v[46:47], off offset:32
	global_load_dwordx4 v[42:45], v[46:47], off offset:16
	s_nop 0
	global_load_dwordx4 v[46:49], v[46:47], off
	v_ashrrev_i32_e32 v33, 31, v32
	s_movk_i32 s0, 0x3f4f
	v_cmp_lt_i32_e32 vcc, s0, v144
	s_waitcnt vmcnt(2)
	v_mov_b32_e32 v60, v39
	v_mov_b32_e32 v61, v41
	s_waitcnt vmcnt(0)
; __device__ __forceinline__ u32x4 pack8(const f32x4 a, const f32x4 b) { u32x4 w; w.x = cvt_pk_bf16(a[0], a[1]); w.y = cvt_pk_bf16(a[2], a[3]); w.z = cvt_pk_bf16(b[0], b[1]); w.w = cvt_pk_bf16(b[2], b[3]); return w; }
;     __device__ __forceinline__ void operator()(const f32x4 (&acc)[2][2][4][2], const Unit& u, int wr, int wc, int fr, int fq) const {
;     ...
;                 for (int m = 0; m < 4; ++m) { const int row = row0 + ai * HALF + m * 16;
;                     const int pidx = row < 16384 ? 16 + (row & 2047) : row < 16512 ? ((row - 16384) & 15) : row < 17536 ? 2064 + ((row - 16512) & 7) : 0;
;                     const f32x4* tp = (const f32x4*)(tab + ((size_t)pidx * 64 + dl) * 2);
;                     const f32x4 t0 = tp[0], t1 = tp[1], t2 = tp[2], t3 = tp[3];
;                     const f32x4 c0 = {t0.x, t0.z, t1.x, t1.z}, s0 = {t0.y, t0.w, t1.y, t1.w}, c1 = {t2.x, t2.z, t3.x, t3.z}, s1 = {t2.y, t2.w, t3.y, t3.w};
;                     const f32x4 a0 = acc[ai][0][m][0], a1 = acc[ai][0][m][1], b0 = acc[ai][1][m][0], b1 = acc[ai][1][m][1];
;                     const f32x4 o10 = (a0 * c0 - b0 * s0) * ksc, o11 = (a1 * c1 - b1 * s1) * ksc, o20 = (a0 * s0 + b0 * c0) * ksc, o21 = (a1 * s1 + b1 * c1) * ksc;
;                     bf16_t* rowp = base + (size_t)row * 1024;
;                     *(u32x4*)rowp = pack8(o10, o11); *(u32x4*)(rowp + 64) = pack8(o20, o21);
;                     if (m & 1) asm volatile("" ::: "memory"); }
	v_mov_b32_e32 v54, v47
	v_mov_b32_e32 v55, v49
	v_pk_mul_f32 v[56:57], v[20:21], v[54:55]
	v_mov_b32_e32 v47, v48
	v_mov_b32_e32 v39, v40
	v_pk_fma_f32 v[48:49], v[28:29], v[46:47], v[56:57] neg_lo:[0,0,1] neg_hi:[0,0,1]
	v_mov_b32_e32 v56, v35
	v_mov_b32_e32 v57, v37
	v_pk_mul_f32 v[62:63], v[16:17], v[60:61]
	v_mov_b32_e32 v35, v36
	v_pk_mul_f32 v[16:17], v[16:17], v[38:39]
	v_mov_b32_e32 v50, v43
	v_mov_b32_e32 v51, v45
	v_pk_mul_f32 v[58:59], v[18:19], v[56:57]
	v_pk_mul_f32 v[18:19], v[18:19], v[34:35]
	v_pk_fma_f32 v[16:17], v[24:25], v[60:61], v[16:17]
	v_pk_mul_f32 v[52:53], v[22:23], v[50:51]
	v_mov_b32_e32 v43, v44
	v_pk_fma_f32 v[36:37], v[26:27], v[34:35], v[58:59] neg_lo:[0,0,1] neg_hi:[0,0,1]
	v_pk_mul_f32 v[20:21], v[20:21], v[46:47]
	v_pk_fma_f32 v[18:19], v[26:27], v[56:57], v[18:19]
	v_pk_mul_f32 v[26:27], v[146:147], v[16:17]
	v_lshlrev_b64 v[16:17], 11, v[32:33]
	v_pk_fma_f32 v[44:45], v[30:31], v[42:43], v[52:53] neg_lo:[0,0,1] neg_hi:[0,0,1]
	v_mov_b32_e32 v52, v146
	v_mov_b32_e32 v53, v146
	v_pk_mul_f32 v[48:49], v[146:147], v[48:49]
	v_pk_fma_f32 v[40:41], v[24:25], v[38:39], v[62:63] neg_lo:[0,0,1] neg_hi:[0,0,1]
	v_pk_mul_f32 v[22:23], v[22:23], v[42:43]
	v_pk_fma_f32 v[20:21], v[28:29], v[54:55], v[20:21]
	v_lshl_add_u64 v[28:29], v[148:149], 0, v[16:17]
	v_cvt_pk_bf16_f32 v16, v48, v49
	v_pk_mul_f32 v[44:45], v[52:53], v[44:45]
	v_pk_mul_f32 v[36:37], v[52:53], v[36:37]
	v_pk_mul_f32 v[40:41], v[146:147], v[40:41]
	v_pk_fma_f32 v[22:23], v[30:31], v[50:51], v[22:23]
	v_pk_mul_f32 v[20:21], v[146:147], v[20:21]
	v_pk_mul_f32 v[24:25], v[52:53], v[18:19]
	v_cvt_pk_bf16_f32 v17, v44, v45
	v_cvt_pk_bf16_f32 v18, v40, v41
	v_cvt_pk_bf16_f32 v19, v36, v37
	global_store_dwordx4 v[28:29], v[16:19], off nt
	v_pk_mul_f32 v[22:23], v[52:53], v[22:23]
	s_nop 0
	v_cvt_pk_bf16_f32 v16, v20, v21
	v_cvt_pk_bf16_f32 v17, v22, v23
	v_cvt_pk_bf16_f32 v18, v26, v27
	v_cvt_pk_bf16_f32 v19, v24, v25
	global_store_dwordx4 v[28:29], v[16:19], off offset:128 nt
	s_nop 1
	v_add_u32_e32 v16, 0xb0, v144
	s_and_saveexec_b64 s[0:1], vcc
	s_xor_b64 s[0:1], exec, s[0:1]
	s_movk_i32 s9, 0x4480
	v_cmp_gt_u32_e32 vcc, s9, v16
	s_movk_i32 s9, 0x4080
	s_nop 0
	v_cndmask_b32_e32 v17, 0, v160, vcc
	v_cmp_gt_u32_e32 vcc, s9, v16
	s_nop 1
	v_cndmask_b32_e32 v18, v17, v158, vcc
	s_andn2_saveexec_b64 s[0:1], s[0:1]
	v_and_b32_e32 v17, 0x7ff, v16
	v_add_u32_e32 v18, 16, v17
	s_or_b64 exec, exec, s[0:1]
	v_mov_b32_e32 v19, v189
	v_lshlrev_b64 v[18:19], 9, v[18:19]
	v_lshl_add_u64 v[30:31], v[138:139], 0, v[18:19]
	global_load_dwordx4 v[18:21], v[30:31], off offset:16
	global_load_dwordx4 v[22:25], v[30:31], off
	global_load_dwordx4 v[26:29], v[30:31], off offset:48
	s_nop 0
	global_load_dwordx4 v[30:33], v[30:31], off offset:32
	v_ashrrev_i32_e32 v17, 31, v16
	v_mov_b32_e32 v34, v146
	v_mov_b32_e32 v35, v146
	v_lshlrev_b64 v[16:17], 11, v[16:17]
	v_lshl_add_u64 v[16:17], v[148:149], 0, v[16:17]
	s_waitcnt vmcnt(3)
	v_mov_b32_e32 v36, v19
	v_mov_b32_e32 v37, v21
	s_waitcnt vmcnt(2)
	v_mov_b32_e32 v38, v23
	v_mov_b32_e32 v39, v25
	v_mov_b32_e32 v23, v24
	v_mov_b32_e32 v19, v20
	s_waitcnt vmcnt(1)
	v_mov_b32_e32 v20, v27
	v_mov_b32_e32 v21, v29
	s_waitcnt vmcnt(0)
	v_mov_b32_e32 v24, v31
	v_mov_b32_e32 v25, v33
	v_mov_b32_e32 v31, v32
	v_mov_b32_e32 v27, v28
	v_pk_mul_f32 v[28:29], v[6:7], v[36:37]
	v_pk_mul_f32 v[32:33], v[4:5], v[38:39]
	v_pk_mul_f32 v[40:41], v[2:3], v[20:21]
	v_pk_mul_f32 v[42:43], v[0:1], v[24:25]
	v_pk_mul_f32 v[2:3], v[2:3], v[26:27]
	v_pk_mul_f32 v[0:1], v[0:1], v[30:31]
	v_pk_mul_f32 v[6:7], v[6:7], v[18:19]
	v_pk_mul_f32 v[4:5], v[4:5], v[22:23]
	v_pk_fma_f32 v[22:23], v[12:13], v[22:23], v[32:33] neg_lo:[0,0,1] neg_hi:[0,0,1]
	v_pk_fma_f32 v[18:19], v[14:15], v[18:19], v[28:29] neg_lo:[0,0,1] neg_hi:[0,0,1]
	v_pk_fma_f32 v[28:29], v[8:9], v[30:31], v[42:43] neg_lo:[0,0,1] neg_hi:[0,0,1]
	v_pk_fma_f32 v[26:27], v[10:11], v[26:27], v[40:41] neg_lo:[0,0,1] neg_hi:[0,0,1]
	v_pk_fma_f32 v[0:1], v[8:9], v[24:25], v[0:1]
	v_pk_fma_f32 v[2:3], v[10:11], v[20:21], v[2:3]
	v_pk_fma_f32 v[4:5], v[12:13], v[38:39], v[4:5]
	v_pk_fma_f32 v[6:7], v[14:15], v[36:37], v[6:7]
	v_pk_mul_f32 v[8:9], v[34:35], v[18:19]
	v_pk_mul_f32 v[10:11], v[146:147], v[22:23]
	v_pk_mul_f32 v[12:13], v[34:35], v[26:27]
	v_pk_mul_f32 v[14:15], v[146:147], v[28:29]
	v_pk_mul_f32 v[18:19], v[34:35], v[2:3]
	v_pk_mul_f32 v[20:21], v[146:147], v[0:1]
	v_cvt_pk_bf16_f32 v0, v10, v11
	v_cvt_pk_bf16_f32 v1, v8, v9
	v_cvt_pk_bf16_f32 v2, v14, v15
	v_cvt_pk_bf16_f32 v3, v12, v13
	v_pk_mul_f32 v[6:7], v[34:35], v[6:7]
	v_pk_mul_f32 v[4:5], v[146:147], v[4:5]
	global_store_dwordx4 v[16:17], v[0:3], off nt
	s_nop 1
	v_cvt_pk_bf16_f32 v0, v4, v5
	v_cvt_pk_bf16_f32 v1, v6, v7
	v_cvt_pk_bf16_f32 v2, v20, v21
	v_cvt_pk_bf16_f32 v3, v18, v19
	global_store_dwordx4 v[16:17], v[0:3], off offset:128 nt
	s_andn2_b64 vcc, exec, s[4:5]
	s_mov_b64 s[0:1], -1
	s_cbranch_vccnz .LBB0_127
	s_branch .LBB0_261

; __device__ __forceinline__ float sigm(float x) { return __builtin_amdgcn_rcpf(1.f + __expf(-x)); }
; __device__ __forceinline__ float silu(float x) { return x * __builtin_amdgcn_rcpf(1.f + __expf(-x)); }
; __device__ __forceinline__ u32x4 pack8(const f32x4 a, const f32x4 b) { u32x4 w; w.x = cvt_pk_bf16(a[0], a[1]); w.y = cvt_pk_bf16(a[2], a[3]); w.z = cvt_pk_bf16(b[0], b[1]); w.w = cvt_pk_bf16(b[2], b[3]); return w; }
;     __device__ __forceinline__ void operator()(const f32x4 (&acc)[2][2][4][2], const Unit& u, int wr, int wc, int fr, int fq) const {
;     ...
;             if (pn < 20) { buf = pn >> 2; colt = (pn & 3) * 256; act = (buf == 3) ? 1 : 0; }
;             else { buf = 6 + ((pn - 28) >> 2); colt = ((pn - 28) & 3) * 256; act = 2; }
;             bf16_t* base = P + (size_t)buf * bstride + colt + wc * 32 + 8 * fq;
; #pragma unroll
;             for (int ai = 0; ai < 2; ++ai)
; #pragma unroll
;                 for (int m = 0; m < 4; ++m) { bf16_t* rowp = base + (size_t)(row0 + ai * HALF + m * 16) * 1024;
; #pragma unroll
;                     for (int bj = 0; bj < 2; ++bj) { f32x4 v0 = acc[ai][bj][m][0], v1 = acc[ai][bj][m][1];
;                         if (act == 1) {
; #pragma unroll
;                             for (int j = 0; j < 4; ++j) { v0[j] = silu(v0[j]); v1[j] = silu(v1[j]); } }
;                         else if (act == 2) {
; #pragma unroll
;                             for (int j = 0; j < 4; ++j) { v0[j] = sigm(v0[j]); v1[j] = sigm(v1[j]); } }
;                         *(u32x4*)(rowp + bj * HALF) = pack8(v0, v1); } }
.LBB0_181:
	s_mul_hi_u32 s0, s16, 0x2280000
	s_mul_i32 s1, s16, 0x2280000
	v_readlane_b32 s16, v254, 19
	s_add_u32 s1, s16, s1
	v_readlane_b32 s16, v254, 20
	s_addc_u32 s0, s16, s0
	s_lshl_b32 s16, s37, 9
	s_and_b32 s16, s16, 0x600
	s_add_u32 s1, s1, s16
	s_addc_u32 s16, s0, 0
	s_lshl_b32 s0, s29, 1
	s_add_u32 s0, s1, s0
	s_addc_u32 s1, s16, 0
	v_lshlrev_b32_e32 v146, 1, v136
	v_mov_b32_e32 v147, v189
	v_ashrrev_i32_e32 v145, 31, v144
	v_lshl_add_u64 v[146:147], s[0:1], 0, v[146:147]
	v_lshlrev_b64 v[148:149], 11, v[144:145]
	v_lshl_add_u64 v[148:149], v[146:147], 0, v[148:149]
	v_cvt_pk_bf16_f32 v150, v150, v151
	v_cvt_pk_bf16_f32 v151, v154, v155
	v_cvt_pk_bf16_f32 v152, v152, v153
	v_cvt_pk_bf16_f32 v153, v156, v157
	s_cmp_gt_i32 s11, 1
	s_mov_b64 s[0:1], -1
	global_store_dwordx4 v[148:149], v[150:153], off nt
	s_cbranch_scc0 .LBB0_183
	s_nop 0
	v_mul_f32_e32 v151, 0xbfb8aa3b, v112
	v_mul_f32_e32 v152, 0xbfb8aa3b, v117
	v_exp_f32_e32 v151, v151
	v_exp_f32_e32 v153, v152
	v_mul_f32_e32 v152, 0xbfb8aa3b, v113
	v_exp_f32_e32 v154, v152
	v_add_f32_e32 v151, 1.0, v151
	v_mul_f32_e32 v155, 0xbfb8aa3b, v114
	v_mul_f32_e32 v156, 0xbfb8aa3b, v119
	v_mul_f32_e32 v150, 0xbfb8aa3b, v116
	v_rcp_f32_e32 v152, v151
	v_add_f32_e32 v151, 1.0, v153
	v_add_f32_e32 v153, 1.0, v154
	v_mul_f32_e32 v154, 0xbfb8aa3b, v118
	v_exp_f32_e32 v155, v155
	v_exp_f32_e32 v157, v156
	v_mul_f32_e32 v156, 0xbfb8aa3b, v115
	v_exp_f32_e32 v150, v150
	v_exp_f32_e32 v154, v154
	v_exp_f32_e32 v162, v156
	v_add_f32_e32 v155, 1.0, v155
	v_add_f32_e32 v150, 1.0, v150
	v_add_f32_e32 v154, 1.0, v154
	v_rcp_f32_e32 v156, v155
	v_add_f32_e32 v155, 1.0, v157
	v_add_f32_e32 v157, 1.0, v162
	v_rcp_f32_e32 v150, v150
	v_rcp_f32_e32 v151, v151
	v_rcp_f32_e32 v153, v153
	v_rcp_f32_e32 v154, v154
	v_rcp_f32_e32 v155, v155
	v_rcp_f32_e32 v157, v157
	s_mov_b64 s[0:1], 0

; __device__ __forceinline__ float sigm(float x) { return __builtin_amdgcn_rcpf(1.f + __expf(-x)); }
; __device__ __forceinline__ float silu(float x) { return x * __builtin_amdgcn_rcpf(1.f + __expf(-x)); }
; __device__ __forceinline__ u32x4 pack8(const f32x4 a, const f32x4 b) { u32x4 w; w.x = cvt_pk_bf16(a[0], a[1]); w.y = cvt_pk_bf16(a[2], a[3]); w.z = cvt_pk_bf16(b[0], b[1]); w.w = cvt_pk_bf16(b[2], b[3]); return w; }
;     __device__ __forceinline__ void operator()(const f32x4 (&acc)[2][2][4][2], const Unit& u, int wr, int wc, int fr, int fq) const {
;     ...
;                 for (int m = 0; m < 4; ++m) { bf16_t* rowp = base + (size_t)(row0 + ai * HALF + m * 16) * 1024;
; #pragma unroll
;                     for (int bj = 0; bj < 2; ++bj) { f32x4 v0 = acc[ai][bj][m][0], v1 = acc[ai][bj][m][1];
;                         if (act == 1) {
; #pragma unroll
;                             for (int j = 0; j < 4; ++j) { v0[j] = silu(v0[j]); v1[j] = silu(v1[j]); } }
;                         else if (act == 2) {
; #pragma unroll
;                             for (int j = 0; j < 4; ++j) { v0[j] = sigm(v0[j]); v1[j] = sigm(v1[j]); } }
;                         *(u32x4*)(rowp + bj * HALF) = pack8(v0, v1); } }
.LBB0_186:
	v_cvt_pk_bf16_f32 v150, v150, v151
	v_cvt_pk_bf16_f32 v151, v154, v155
	s_nop 0
	v_cvt_pk_bf16_f32 v152, v152, v153
	v_cvt_pk_bf16_f32 v153, v156, v157
	s_cmp_gt_i32 s11, 1
	s_mov_b64 s[0:1], -1
	global_store_dwordx4 v[148:149], v[150:153], off offset:256 nt
	s_cbranch_scc0 .LBB0_188
	v_mul_f32_e32 v148, 0xbfb8aa3b, v108
	v_exp_f32_e32 v148, v148
	v_mul_f32_e32 v149, 0xbfb8aa3b, v104
	v_exp_f32_e32 v149, v149
	v_mul_f32_e32 v151, 0xbfb8aa3b, v105
	v_add_f32_e32 v148, 1.0, v148
	v_rcp_f32_e32 v150, v148
	v_mul_f32_e32 v148, 0xbfb8aa3b, v109
	v_exp_f32_e32 v148, v148
	v_exp_f32_e32 v153, v151
	v_add_f32_e32 v149, 1.0, v149
	v_rcp_f32_e32 v152, v149
	v_add_f32_e32 v148, 1.0, v148
	v_mul_f32_e32 v149, 0xbfb8aa3b, v110
	v_rcp_f32_e32 v151, v148
	v_add_f32_e32 v148, 1.0, v153
	v_exp_f32_e32 v149, v149
	v_mul_f32_e32 v153, 0xbfb8aa3b, v106
	v_exp_f32_e32 v155, v153
	v_rcp_f32_e32 v153, v148
	v_add_f32_e32 v148, 1.0, v149
	v_mul_f32_e32 v149, 0xbfb8aa3b, v111
	v_rcp_f32_e32 v154, v148
	v_add_f32_e32 v148, 1.0, v155
	v_exp_f32_e32 v149, v149
	v_mul_f32_e32 v155, 0xbfb8aa3b, v107
	v_exp_f32_e32 v157, v155
	v_rcp_f32_e32 v156, v148
	v_add_f32_e32 v148, 1.0, v149
	v_rcp_f32_e32 v155, v148
	v_add_f32_e32 v148, 1.0, v157
	v_rcp_f32_e32 v157, v148
	s_mov_b64 s[0:1], 0

; __device__ __forceinline__ float sigm(float x) { return __builtin_amdgcn_rcpf(1.f + __expf(-x)); }
; __device__ __forceinline__ float silu(float x) { return x * __builtin_amdgcn_rcpf(1.f + __expf(-x)); }
; __device__ __forceinline__ u32x4 pack8(const f32x4 a, const f32x4 b) { u32x4 w; w.x = cvt_pk_bf16(a[0], a[1]); w.y = cvt_pk_bf16(a[2], a[3]); w.z = cvt_pk_bf16(b[0], b[1]); w.w = cvt_pk_bf16(b[2], b[3]); return w; }
;     __device__ __forceinline__ void operator()(const f32x4 (&acc)[2][2][4][2], const Unit& u, int wr, int wc, int fr, int fq) const {
;     ...
;                 for (int m = 0; m < 4; ++m) { bf16_t* rowp = base + (size_t)(row0 + ai * HALF + m * 16) * 1024;
; #pragma unroll
;                     for (int bj = 0; bj < 2; ++bj) { f32x4 v0 = acc[ai][bj][m][0], v1 = acc[ai][bj][m][1];
;                         if (act == 1) {
; #pragma unroll
;                             for (int j = 0; j < 4; ++j) { v0[j] = silu(v0[j]); v1[j] = silu(v1[j]); } }
;                         else if (act == 2) {
; #pragma unroll
;                             for (int j = 0; j < 4; ++j) { v0[j] = sigm(v0[j]); v1[j] = sigm(v1[j]); } }
;                         *(u32x4*)(rowp + bj * HALF) = pack8(v0, v1); } }
.LBB0_191:
	v_or_b32_e32 v148, 16, v144
	v_ashrrev_i32_e32 v149, 31, v148
	v_lshlrev_b64 v[148:149], 11, v[148:149]
	v_lshl_add_u64 v[148:149], v[146:147], 0, v[148:149]
	v_cvt_pk_bf16_f32 v150, v150, v151
	v_cvt_pk_bf16_f32 v151, v154, v155
	v_cvt_pk_bf16_f32 v152, v152, v153
	v_cvt_pk_bf16_f32 v153, v156, v157
	s_cmp_gt_i32 s11, 1
	s_mov_b64 s[0:1], -1
	global_store_dwordx4 v[148:149], v[150:153], off nt
	s_cbranch_scc0 .LBB0_193
	s_nop 0
	v_mul_f32_e32 v151, 0xbfb8aa3b, v96
	v_mul_f32_e32 v152, 0xbfb8aa3b, v101
	v_exp_f32_e32 v151, v151
	v_exp_f32_e32 v153, v152
	v_mul_f32_e32 v152, 0xbfb8aa3b, v97
	v_exp_f32_e32 v154, v152
	v_add_f32_e32 v151, 1.0, v151
	v_mul_f32_e32 v155, 0xbfb8aa3b, v98
	v_mul_f32_e32 v156, 0xbfb8aa3b, v103
	v_mul_f32_e32 v150, 0xbfb8aa3b, v100
	v_rcp_f32_e32 v152, v151
	v_add_f32_e32 v151, 1.0, v153
	v_add_f32_e32 v153, 1.0, v154
	v_mul_f32_e32 v154, 0xbfb8aa3b, v102
	v_exp_f32_e32 v155, v155
	v_exp_f32_e32 v157, v156
	v_mul_f32_e32 v156, 0xbfb8aa3b, v99
	v_exp_f32_e32 v150, v150
	v_exp_f32_e32 v154, v154
	v_exp_f32_e32 v162, v156
	v_add_f32_e32 v155, 1.0, v155
	v_add_f32_e32 v150, 1.0, v150
	v_add_f32_e32 v154, 1.0, v154
	v_rcp_f32_e32 v156, v155
	v_add_f32_e32 v155, 1.0, v157
	v_add_f32_e32 v157, 1.0, v162
	v_rcp_f32_e32 v150, v150
	v_rcp_f32_e32 v151, v151
	v_rcp_f32_e32 v153, v153
	v_rcp_f32_e32 v154, v154
	v_rcp_f32_e32 v155, v155
	v_rcp_f32_e32 v157, v157
	s_mov_b64 s[0:1], 0

; __device__ __forceinline__ float sigm(float x) { return __builtin_amdgcn_rcpf(1.f + __expf(-x)); }
; __device__ __forceinline__ float silu(float x) { return x * __builtin_amdgcn_rcpf(1.f + __expf(-x)); }
; __device__ __forceinline__ u32x4 pack8(const f32x4 a, const f32x4 b) { u32x4 w; w.x = cvt_pk_bf16(a[0], a[1]); w.y = cvt_pk_bf16(a[2], a[3]); w.z = cvt_pk_bf16(b[0], b[1]); w.w = cvt_pk_bf16(b[2], b[3]); return w; }
;     __device__ __forceinline__ void operator()(const f32x4 (&acc)[2][2][4][2], const Unit& u, int wr, int wc, int fr, int fq) const {
;     ...
;                 for (int m = 0; m < 4; ++m) { bf16_t* rowp = base + (size_t)(row0 + ai * HALF + m * 16) * 1024;
; #pragma unroll
;                     for (int bj = 0; bj < 2; ++bj) { f32x4 v0 = acc[ai][bj][m][0], v1 = acc[ai][bj][m][1];
;                         if (act == 1) {
; #pragma unroll
;                             for (int j = 0; j < 4; ++j) { v0[j] = silu(v0[j]); v1[j] = silu(v1[j]); } }
;                         else if (act == 2) {
; #pragma unroll
;                             for (int j = 0; j < 4; ++j) { v0[j] = sigm(v0[j]); v1[j] = sigm(v1[j]); } }
;                         *(u32x4*)(rowp + bj * HALF) = pack8(v0, v1); } }
.LBB0_196:
	v_cvt_pk_bf16_f32 v150, v150, v151
	v_cvt_pk_bf16_f32 v151, v154, v155
	s_nop 0
	v_cvt_pk_bf16_f32 v152, v152, v153
	v_cvt_pk_bf16_f32 v153, v156, v157
	s_cmp_gt_i32 s11, 1
	s_mov_b64 s[0:1], -1
	global_store_dwordx4 v[148:149], v[150:153], off offset:256 nt
	s_cbranch_scc0 .LBB0_198
	v_mul_f32_e32 v148, 0xbfb8aa3b, v92
	v_exp_f32_e32 v148, v148
	v_mul_f32_e32 v149, 0xbfb8aa3b, v88
	v_exp_f32_e32 v149, v149
	v_mul_f32_e32 v151, 0xbfb8aa3b, v89
	v_add_f32_e32 v148, 1.0, v148
	v_rcp_f32_e32 v150, v148
	v_mul_f32_e32 v148, 0xbfb8aa3b, v93
	v_exp_f32_e32 v148, v148
	v_exp_f32_e32 v153, v151
	v_add_f32_e32 v149, 1.0, v149
	v_rcp_f32_e32 v152, v149
	v_add_f32_e32 v148, 1.0, v148
	v_mul_f32_e32 v149, 0xbfb8aa3b, v94
	v_rcp_f32_e32 v151, v148
	v_add_f32_e32 v148, 1.0, v153
	v_exp_f32_e32 v149, v149
	v_mul_f32_e32 v153, 0xbfb8aa3b, v90
	v_exp_f32_e32 v155, v153
	v_rcp_f32_e32 v153, v148
	v_add_f32_e32 v148, 1.0, v149
	v_mul_f32_e32 v149, 0xbfb8aa3b, v95
	v_rcp_f32_e32 v154, v148
	v_add_f32_e32 v148, 1.0, v155
	v_exp_f32_e32 v149, v149
	v_mul_f32_e32 v155, 0xbfb8aa3b, v91
	v_exp_f32_e32 v157, v155
	v_rcp_f32_e32 v156, v148
	v_add_f32_e32 v148, 1.0, v149
	v_rcp_f32_e32 v155, v148
	v_add_f32_e32 v148, 1.0, v157
	v_rcp_f32_e32 v157, v148
	s_mov_b64 s[0:1], 0

; __device__ __forceinline__ float sigm(float x) { return __builtin_amdgcn_rcpf(1.f + __expf(-x)); }
; __device__ __forceinline__ float silu(float x) { return x * __builtin_amdgcn_rcpf(1.f + __expf(-x)); }
; __device__ __forceinline__ u32x4 pack8(const f32x4 a, const f32x4 b) { u32x4 w; w.x = cvt_pk_bf16(a[0], a[1]); w.y = cvt_pk_bf16(a[2], a[3]); w.z = cvt_pk_bf16(b[0], b[1]); w.w = cvt_pk_bf16(b[2], b[3]); return w; }
;     __device__ __forceinline__ void operator()(const f32x4 (&acc)[2][2][4][2], const Unit& u, int wr, int wc, int fr, int fq) const {
;     ...
;                 for (int m = 0; m < 4; ++m) { bf16_t* rowp = base + (size_t)(row0 + ai * HALF + m * 16) * 1024;
; #pragma unroll
;                     for (int bj = 0; bj < 2; ++bj) { f32x4 v0 = acc[ai][bj][m][0], v1 = acc[ai][bj][m][1];
;                         if (act == 1) {
; #pragma unroll
;                             for (int j = 0; j < 4; ++j) { v0[j] = silu(v0[j]); v1[j] = silu(v1[j]); } }
;                         else if (act == 2) {
; #pragma unroll
;                             for (int j = 0; j < 4; ++j) { v0[j] = sigm(v0[j]); v1[j] = sigm(v1[j]); } }
;                         *(u32x4*)(rowp + bj * HALF) = pack8(v0, v1); } }
.LBB0_201:
	v_or_b32_e32 v148, 32, v144
	v_ashrrev_i32_e32 v149, 31, v148
	v_lshlrev_b64 v[148:149], 11, v[148:149]
	v_lshl_add_u64 v[148:149], v[146:147], 0, v[148:149]
	v_cvt_pk_bf16_f32 v150, v150, v151
	v_cvt_pk_bf16_f32 v151, v154, v155
	v_cvt_pk_bf16_f32 v152, v152, v153
	v_cvt_pk_bf16_f32 v153, v156, v157
	s_cmp_gt_i32 s11, 1
	s_mov_b64 s[0:1], -1
	global_store_dwordx4 v[148:149], v[150:153], off nt
	s_cbranch_scc0 .LBB0_203
	s_nop 0
	v_mul_f32_e32 v151, 0xbfb8aa3b, v80
	v_mul_f32_e32 v152, 0xbfb8aa3b, v85
	v_exp_f32_e32 v151, v151
	v_exp_f32_e32 v153, v152
	v_mul_f32_e32 v152, 0xbfb8aa3b, v81
	v_exp_f32_e32 v154, v152
	v_add_f32_e32 v151, 1.0, v151
	v_mul_f32_e32 v155, 0xbfb8aa3b, v82
	v_mul_f32_e32 v156, 0xbfb8aa3b, v87
	v_mul_f32_e32 v150, 0xbfb8aa3b, v84
	v_rcp_f32_e32 v152, v151
	v_add_f32_e32 v151, 1.0, v153
	v_add_f32_e32 v153, 1.0, v154
	v_mul_f32_e32 v154, 0xbfb8aa3b, v86
	v_exp_f32_e32 v155, v155
	v_exp_f32_e32 v157, v156
	v_mul_f32_e32 v156, 0xbfb8aa3b, v83
	v_exp_f32_e32 v150, v150
	v_exp_f32_e32 v154, v154
	v_exp_f32_e32 v162, v156
	v_add_f32_e32 v155, 1.0, v155
	v_add_f32_e32 v150, 1.0, v150
	v_add_f32_e32 v154, 1.0, v154
	v_rcp_f32_e32 v156, v155
	v_add_f32_e32 v155, 1.0, v157
	v_add_f32_e32 v157, 1.0, v162
	v_rcp_f32_e32 v150, v150
	v_rcp_f32_e32 v151, v151
	v_rcp_f32_e32 v153, v153
	v_rcp_f32_e32 v154, v154
	v_rcp_f32_e32 v155, v155
	v_rcp_f32_e32 v157, v157
	s_mov_b64 s[0:1], 0

; __device__ __forceinline__ float sigm(float x) { return __builtin_amdgcn_rcpf(1.f + __expf(-x)); }
; __device__ __forceinline__ float silu(float x) { return x * __builtin_amdgcn_rcpf(1.f + __expf(-x)); }
; __device__ __forceinline__ u32x4 pack8(const f32x4 a, const f32x4 b) { u32x4 w; w.x = cvt_pk_bf16(a[0], a[1]); w.y = cvt_pk_bf16(a[2], a[3]); w.z = cvt_pk_bf16(b[0], b[1]); w.w = cvt_pk_bf16(b[2], b[3]); return w; }
;     __device__ __forceinline__ void operator()(const f32x4 (&acc)[2][2][4][2], const Unit& u, int wr, int wc, int fr, int fq) const {
;     ...
;                 for (int m = 0; m < 4; ++m) { bf16_t* rowp = base + (size_t)(row0 + ai * HALF + m * 16) * 1024;
; #pragma unroll
;                     for (int bj = 0; bj < 2; ++bj) { f32x4 v0 = acc[ai][bj][m][0], v1 = acc[ai][bj][m][1];
;                         if (act == 1) {
; #pragma unroll
;                             for (int j = 0; j < 4; ++j) { v0[j] = silu(v0[j]); v1[j] = silu(v1[j]); } }
;                         else if (act == 2) {
; #pragma unroll
;                             for (int j = 0; j < 4; ++j) { v0[j] = sigm(v0[j]); v1[j] = sigm(v1[j]); } }
;                         *(u32x4*)(rowp + bj * HALF) = pack8(v0, v1); } }
.LBB0_206:
	v_cvt_pk_bf16_f32 v150, v150, v151
	v_cvt_pk_bf16_f32 v151, v154, v155
	s_nop 0
	v_cvt_pk_bf16_f32 v152, v152, v153
	v_cvt_pk_bf16_f32 v153, v156, v157
	s_cmp_gt_i32 s11, 1
	s_mov_b64 s[0:1], -1
	global_store_dwordx4 v[148:149], v[150:153], off offset:256 nt
	s_cbranch_scc0 .LBB0_208
	v_mul_f32_e32 v148, 0xbfb8aa3b, v76
	v_exp_f32_e32 v148, v148
	v_mul_f32_e32 v149, 0xbfb8aa3b, v72
	v_exp_f32_e32 v149, v149
	v_mul_f32_e32 v151, 0xbfb8aa3b, v73
	v_add_f32_e32 v148, 1.0, v148
	v_rcp_f32_e32 v150, v148
	v_mul_f32_e32 v148, 0xbfb8aa3b, v77
	v_exp_f32_e32 v148, v148
	v_exp_f32_e32 v153, v151
	v_add_f32_e32 v149, 1.0, v149
	v_rcp_f32_e32 v152, v149
	v_add_f32_e32 v148, 1.0, v148
	v_mul_f32_e32 v149, 0xbfb8aa3b, v78
	v_rcp_f32_e32 v151, v148
	v_add_f32_e32 v148, 1.0, v153
	v_exp_f32_e32 v149, v149
	v_mul_f32_e32 v153, 0xbfb8aa3b, v74
	v_exp_f32_e32 v155, v153
	v_rcp_f32_e32 v153, v148
	v_add_f32_e32 v148, 1.0, v149
	v_mul_f32_e32 v149, 0xbfb8aa3b, v79
	v_rcp_f32_e32 v154, v148
	v_add_f32_e32 v148, 1.0, v155
	v_exp_f32_e32 v149, v149
	v_mul_f32_e32 v155, 0xbfb8aa3b, v75
	v_exp_f32_e32 v157, v155
	v_rcp_f32_e32 v156, v148
	v_add_f32_e32 v148, 1.0, v149
	v_rcp_f32_e32 v155, v148
	v_add_f32_e32 v148, 1.0, v157
	v_rcp_f32_e32 v157, v148
	s_mov_b64 s[0:1], 0

; __device__ __forceinline__ float sigm(float x) { return __builtin_amdgcn_rcpf(1.f + __expf(-x)); }
; __device__ __forceinline__ float silu(float x) { return x * __builtin_amdgcn_rcpf(1.f + __expf(-x)); }
; __device__ __forceinline__ u32x4 pack8(const f32x4 a, const f32x4 b) { u32x4 w; w.x = cvt_pk_bf16(a[0], a[1]); w.y = cvt_pk_bf16(a[2], a[3]); w.z = cvt_pk_bf16(b[0], b[1]); w.w = cvt_pk_bf16(b[2], b[3]); return w; }
;     __device__ __forceinline__ void operator()(const f32x4 (&acc)[2][2][4][2], const Unit& u, int wr, int wc, int fr, int fq) const {
;     ...
;                 for (int m = 0; m < 4; ++m) { bf16_t* rowp = base + (size_t)(row0 + ai * HALF + m * 16) * 1024;
; #pragma unroll
;                     for (int bj = 0; bj < 2; ++bj) { f32x4 v0 = acc[ai][bj][m][0], v1 = acc[ai][bj][m][1];
;                         if (act == 1) {
; #pragma unroll
;                             for (int j = 0; j < 4; ++j) { v0[j] = silu(v0[j]); v1[j] = silu(v1[j]); } }
;                         else if (act == 2) {
; #pragma unroll
;                             for (int j = 0; j < 4; ++j) { v0[j] = sigm(v0[j]); v1[j] = sigm(v1[j]); } }
;                         *(u32x4*)(rowp + bj * HALF) = pack8(v0, v1); } }
.LBB0_211:
	v_or_b32_e32 v148, 48, v144
	v_ashrrev_i32_e32 v149, 31, v148
	v_lshlrev_b64 v[148:149], 11, v[148:149]
	v_lshl_add_u64 v[148:149], v[146:147], 0, v[148:149]
	v_cvt_pk_bf16_f32 v150, v150, v151
	v_cvt_pk_bf16_f32 v151, v154, v155
	v_cvt_pk_bf16_f32 v152, v152, v153
	v_cvt_pk_bf16_f32 v153, v156, v157
	s_cmp_gt_i32 s11, 1
	s_mov_b64 s[0:1], -1
	global_store_dwordx4 v[148:149], v[150:153], off nt
	s_cbranch_scc0 .LBB0_213
	s_nop 0
	v_mul_f32_e32 v151, 0xbfb8aa3b, v64
	v_mul_f32_e32 v152, 0xbfb8aa3b, v69
	v_exp_f32_e32 v151, v151
	v_exp_f32_e32 v153, v152
	v_mul_f32_e32 v152, 0xbfb8aa3b, v65
	v_exp_f32_e32 v154, v152
	v_add_f32_e32 v151, 1.0, v151
	v_mul_f32_e32 v155, 0xbfb8aa3b, v66
	v_mul_f32_e32 v156, 0xbfb8aa3b, v71
	v_mul_f32_e32 v150, 0xbfb8aa3b, v68
	v_rcp_f32_e32 v152, v151
	v_add_f32_e32 v151, 1.0, v153
	v_add_f32_e32 v153, 1.0, v154
	v_mul_f32_e32 v154, 0xbfb8aa3b, v70
	v_exp_f32_e32 v155, v155
	v_exp_f32_e32 v157, v156
	v_mul_f32_e32 v156, 0xbfb8aa3b, v67
	v_exp_f32_e32 v150, v150
	v_exp_f32_e32 v154, v154
	v_exp_f32_e32 v162, v156
	v_add_f32_e32 v155, 1.0, v155
	v_add_f32_e32 v150, 1.0, v150
	v_add_f32_e32 v154, 1.0, v154
	v_rcp_f32_e32 v156, v155
	v_add_f32_e32 v155, 1.0, v157
	v_add_f32_e32 v157, 1.0, v162
	v_rcp_f32_e32 v150, v150
	v_rcp_f32_e32 v151, v151
	v_rcp_f32_e32 v153, v153
	v_rcp_f32_e32 v154, v154
	v_rcp_f32_e32 v155, v155
	v_rcp_f32_e32 v157, v157
	s_mov_b64 s[0:1], 0

; __device__ __forceinline__ float sigm(float x) { return __builtin_amdgcn_rcpf(1.f + __expf(-x)); }
; __device__ __forceinline__ float silu(float x) { return x * __builtin_amdgcn_rcpf(1.f + __expf(-x)); }
; __device__ __forceinline__ u32x4 pack8(const f32x4 a, const f32x4 b) { u32x4 w; w.x = cvt_pk_bf16(a[0], a[1]); w.y = cvt_pk_bf16(a[2], a[3]); w.z = cvt_pk_bf16(b[0], b[1]); w.w = cvt_pk_bf16(b[2], b[3]); return w; }
;     __device__ __forceinline__ void operator()(const f32x4 (&acc)[2][2][4][2], const Unit& u, int wr, int wc, int fr, int fq) const {
;     ...
;                 for (int m = 0; m < 4; ++m) { bf16_t* rowp = base + (size_t)(row0 + ai * HALF + m * 16) * 1024;
; #pragma unroll
;                     for (int bj = 0; bj < 2; ++bj) { f32x4 v0 = acc[ai][bj][m][0], v1 = acc[ai][bj][m][1];
;                         if (act == 1) {
; #pragma unroll
;                             for (int j = 0; j < 4; ++j) { v0[j] = silu(v0[j]); v1[j] = silu(v1[j]); } }
;                         else if (act == 2) {
; #pragma unroll
;                             for (int j = 0; j < 4; ++j) { v0[j] = sigm(v0[j]); v1[j] = sigm(v1[j]); } }
;                         *(u32x4*)(rowp + bj * HALF) = pack8(v0, v1); } }
.LBB0_216:
	v_cvt_pk_bf16_f32 v150, v150, v151
	v_cvt_pk_bf16_f32 v151, v154, v155
	s_nop 0
	v_cvt_pk_bf16_f32 v152, v152, v153
	v_cvt_pk_bf16_f32 v153, v156, v157
	s_cmp_gt_i32 s11, 1
	s_mov_b64 s[0:1], -1
	global_store_dwordx4 v[148:149], v[150:153], off offset:256 nt
	s_cbranch_scc0 .LBB0_218
	v_mul_f32_e32 v148, 0xbfb8aa3b, v60
	v_exp_f32_e32 v148, v148
	v_mul_f32_e32 v149, 0xbfb8aa3b, v56
	v_exp_f32_e32 v149, v149
	v_mul_f32_e32 v151, 0xbfb8aa3b, v57
	v_add_f32_e32 v148, 1.0, v148
	v_rcp_f32_e32 v150, v148
	v_mul_f32_e32 v148, 0xbfb8aa3b, v61
	v_exp_f32_e32 v148, v148
	v_exp_f32_e32 v153, v151
	v_add_f32_e32 v149, 1.0, v149
	v_rcp_f32_e32 v152, v149
	v_add_f32_e32 v148, 1.0, v148
	v_mul_f32_e32 v149, 0xbfb8aa3b, v62
	v_rcp_f32_e32 v151, v148
	v_add_f32_e32 v148, 1.0, v153
	v_exp_f32_e32 v149, v149
	v_mul_f32_e32 v153, 0xbfb8aa3b, v58
	v_exp_f32_e32 v155, v153
	v_rcp_f32_e32 v153, v148
	v_add_f32_e32 v148, 1.0, v149
	v_mul_f32_e32 v149, 0xbfb8aa3b, v63
	v_rcp_f32_e32 v154, v148
	v_add_f32_e32 v148, 1.0, v155
	v_exp_f32_e32 v149, v149
	v_mul_f32_e32 v155, 0xbfb8aa3b, v59
	v_exp_f32_e32 v157, v155
	v_rcp_f32_e32 v156, v148
	v_add_f32_e32 v148, 1.0, v149
	v_rcp_f32_e32 v155, v148
	v_add_f32_e32 v148, 1.0, v157
	v_rcp_f32_e32 v157, v148
	s_mov_b64 s[0:1], 0

; __device__ __forceinline__ float sigm(float x) { return __builtin_amdgcn_rcpf(1.f + __expf(-x)); }
; __device__ __forceinline__ float silu(float x) { return x * __builtin_amdgcn_rcpf(1.f + __expf(-x)); }
; __device__ __forceinline__ u32x4 pack8(const f32x4 a, const f32x4 b) { u32x4 w; w.x = cvt_pk_bf16(a[0], a[1]); w.y = cvt_pk_bf16(a[2], a[3]); w.z = cvt_pk_bf16(b[0], b[1]); w.w = cvt_pk_bf16(b[2], b[3]); return w; }
;     __device__ __forceinline__ void operator()(const f32x4 (&acc)[2][2][4][2], const Unit& u, int wr, int wc, int fr, int fq) const {
;     ...
;                 for (int m = 0; m < 4; ++m) { bf16_t* rowp = base + (size_t)(row0 + ai * HALF + m * 16) * 1024;
; #pragma unroll
;                     for (int bj = 0; bj < 2; ++bj) { f32x4 v0 = acc[ai][bj][m][0], v1 = acc[ai][bj][m][1];
;                         if (act == 1) {
; #pragma unroll
;                             for (int j = 0; j < 4; ++j) { v0[j] = silu(v0[j]); v1[j] = silu(v1[j]); } }
;                         else if (act == 2) {
; #pragma unroll
;                             for (int j = 0; j < 4; ++j) { v0[j] = sigm(v0[j]); v1[j] = sigm(v1[j]); } }
;                         *(u32x4*)(rowp + bj * HALF) = pack8(v0, v1); } }
.LBB0_221:
	v_lshlrev_b64 v[148:149], 11, v[144:145]
	v_lshl_add_u64 v[162:163], v[146:147], 0, v[148:149]
	s_mov_b64 s[0:1], 0x40000
	v_cvt_pk_bf16_f32 v150, v150, v151
	v_cvt_pk_bf16_f32 v151, v154, v155
	v_add_co_u32_e32 v154, vcc, 0x40000, v162
	v_lshl_add_u64 v[148:149], v[162:163], 0, s[0:1]
	v_cvt_pk_bf16_f32 v152, v152, v153
	v_cvt_pk_bf16_f32 v153, v156, v157
	s_nop 0
	v_addc_co_u32_e32 v155, vcc, 0, v163, vcc
	s_cmp_gt_i32 s11, 1
	s_mov_b64 s[0:1], -1
	global_store_dwordx4 v[154:155], v[150:153], off nt
	s_cbranch_scc0 .LBB0_223
	s_nop 0
	v_mul_f32_e32 v151, 0xbfb8aa3b, v48
	v_mul_f32_e32 v152, 0xbfb8aa3b, v53
	v_exp_f32_e32 v151, v151
	v_exp_f32_e32 v153, v152
	v_mul_f32_e32 v152, 0xbfb8aa3b, v49
	v_exp_f32_e32 v154, v152
	v_add_f32_e32 v151, 1.0, v151
	v_mul_f32_e32 v155, 0xbfb8aa3b, v50
	v_mul_f32_e32 v156, 0xbfb8aa3b, v55
	v_mul_f32_e32 v150, 0xbfb8aa3b, v52
	v_rcp_f32_e32 v152, v151
	v_add_f32_e32 v151, 1.0, v153
	v_add_f32_e32 v153, 1.0, v154
	v_mul_f32_e32 v154, 0xbfb8aa3b, v54
	v_exp_f32_e32 v155, v155
	v_exp_f32_e32 v157, v156
	v_mul_f32_e32 v156, 0xbfb8aa3b, v51
	v_exp_f32_e32 v150, v150
	v_exp_f32_e32 v154, v154
	v_exp_f32_e32 v162, v156
	v_add_f32_e32 v155, 1.0, v155
	v_add_f32_e32 v150, 1.0, v150
	v_add_f32_e32 v154, 1.0, v154
	v_rcp_f32_e32 v156, v155
	v_add_f32_e32 v155, 1.0, v157
	v_add_f32_e32 v157, 1.0, v162
	v_rcp_f32_e32 v150, v150
	v_rcp_f32_e32 v151, v151
	v_rcp_f32_e32 v153, v153
	v_rcp_f32_e32 v154, v154
	v_rcp_f32_e32 v155, v155
	v_rcp_f32_e32 v157, v157
	s_mov_b64 s[0:1], 0

; __device__ __forceinline__ float sigm(float x) { return __builtin_amdgcn_rcpf(1.f + __expf(-x)); }
; __device__ __forceinline__ float silu(float x) { return x * __builtin_amdgcn_rcpf(1.f + __expf(-x)); }
; __device__ __forceinline__ u32x4 pack8(const f32x4 a, const f32x4 b) { u32x4 w; w.x = cvt_pk_bf16(a[0], a[1]); w.y = cvt_pk_bf16(a[2], a[3]); w.z = cvt_pk_bf16(b[0], b[1]); w.w = cvt_pk_bf16(b[2], b[3]); return w; }
;     __device__ __forceinline__ void operator()(const f32x4 (&acc)[2][2][4][2], const Unit& u, int wr, int wc, int fr, int fq) const {
;     ...
;                 for (int m = 0; m < 4; ++m) { bf16_t* rowp = base + (size_t)(row0 + ai * HALF + m * 16) * 1024;
; #pragma unroll
;                     for (int bj = 0; bj < 2; ++bj) { f32x4 v0 = acc[ai][bj][m][0], v1 = acc[ai][bj][m][1];
;                         if (act == 1) {
; #pragma unroll
;                             for (int j = 0; j < 4; ++j) { v0[j] = silu(v0[j]); v1[j] = silu(v1[j]); } }
;                         else if (act == 2) {
; #pragma unroll
;                             for (int j = 0; j < 4; ++j) { v0[j] = sigm(v0[j]); v1[j] = sigm(v1[j]); } }
;                         *(u32x4*)(rowp + bj * HALF) = pack8(v0, v1); } }
.LBB0_226:
	v_cvt_pk_bf16_f32 v150, v150, v151
	v_cvt_pk_bf16_f32 v151, v154, v155
	s_nop 0
	v_cvt_pk_bf16_f32 v152, v152, v153
	v_cvt_pk_bf16_f32 v153, v156, v157
	s_cmp_gt_i32 s11, 1
	s_mov_b64 s[0:1], -1
	global_store_dwordx4 v[148:149], v[150:153], off offset:256 nt
	s_cbranch_scc0 .LBB0_228
	v_mul_f32_e32 v148, 0xbfb8aa3b, v44
	v_exp_f32_e32 v148, v148
	v_mul_f32_e32 v149, 0xbfb8aa3b, v40
	v_exp_f32_e32 v149, v149
	v_mul_f32_e32 v151, 0xbfb8aa3b, v41
	v_add_f32_e32 v148, 1.0, v148
	v_rcp_f32_e32 v150, v148
	v_mul_f32_e32 v148, 0xbfb8aa3b, v45
	v_exp_f32_e32 v148, v148
	v_exp_f32_e32 v153, v151
	v_add_f32_e32 v149, 1.0, v149
	v_rcp_f32_e32 v152, v149
	v_add_f32_e32 v148, 1.0, v148
	v_mul_f32_e32 v149, 0xbfb8aa3b, v46
	v_rcp_f32_e32 v151, v148
	v_add_f32_e32 v148, 1.0, v153
	v_exp_f32_e32 v149, v149
	v_mul_f32_e32 v153, 0xbfb8aa3b, v42
	v_exp_f32_e32 v155, v153
	v_rcp_f32_e32 v153, v148
	v_add_f32_e32 v148, 1.0, v149
	v_mul_f32_e32 v149, 0xbfb8aa3b, v47
	v_rcp_f32_e32 v154, v148
	v_add_f32_e32 v148, 1.0, v155
	v_exp_f32_e32 v149, v149
	v_mul_f32_e32 v155, 0xbfb8aa3b, v43
	v_exp_f32_e32 v157, v155
	v_rcp_f32_e32 v156, v148
	v_add_f32_e32 v148, 1.0, v149
	v_rcp_f32_e32 v155, v148
	v_add_f32_e32 v148, 1.0, v157
	v_rcp_f32_e32 v157, v148
	s_mov_b64 s[0:1], 0

; __device__ __forceinline__ float sigm(float x) { return __builtin_amdgcn_rcpf(1.f + __expf(-x)); }
; __device__ __forceinline__ float silu(float x) { return x * __builtin_amdgcn_rcpf(1.f + __expf(-x)); }
; __device__ __forceinline__ u32x4 pack8(const f32x4 a, const f32x4 b) { u32x4 w; w.x = cvt_pk_bf16(a[0], a[1]); w.y = cvt_pk_bf16(a[2], a[3]); w.z = cvt_pk_bf16(b[0], b[1]); w.w = cvt_pk_bf16(b[2], b[3]); return w; }
;     __device__ __forceinline__ void operator()(const f32x4 (&acc)[2][2][4][2], const Unit& u, int wr, int wc, int fr, int fq) const {
;     ...
;                 for (int m = 0; m < 4; ++m) { bf16_t* rowp = base + (size_t)(row0 + ai * HALF + m * 16) * 1024;
; #pragma unroll
;                     for (int bj = 0; bj < 2; ++bj) { f32x4 v0 = acc[ai][bj][m][0], v1 = acc[ai][bj][m][1];
;                         if (act == 1) {
; #pragma unroll
;                             for (int j = 0; j < 4; ++j) { v0[j] = silu(v0[j]); v1[j] = silu(v1[j]); } }
;                         else if (act == 2) {
; #pragma unroll
;                             for (int j = 0; j < 4; ++j) { v0[j] = sigm(v0[j]); v1[j] = sigm(v1[j]); } }
;                         *(u32x4*)(rowp + bj * HALF) = pack8(v0, v1); } }
.LBB0_231:
	v_lshlrev_b64 v[148:149], 11, v[144:145]
	v_lshl_add_u64 v[162:163], v[146:147], 0, v[148:149]
	s_mov_b64 s[0:1], 0x48000
	v_cvt_pk_bf16_f32 v150, v150, v151
	v_cvt_pk_bf16_f32 v151, v154, v155
	v_add_co_u32_e32 v154, vcc, 0x48000, v162
	v_lshl_add_u64 v[148:149], v[162:163], 0, s[0:1]
	v_cvt_pk_bf16_f32 v152, v152, v153
	v_cvt_pk_bf16_f32 v153, v156, v157
	s_nop 0
	v_addc_co_u32_e32 v155, vcc, 0, v163, vcc
	s_cmp_gt_i32 s11, 1
	s_mov_b64 s[0:1], -1
	global_store_dwordx4 v[154:155], v[150:153], off nt
	s_cbranch_scc0 .LBB0_233
	s_nop 0
	v_mul_f32_e32 v151, 0xbfb8aa3b, v32
	v_mul_f32_e32 v152, 0xbfb8aa3b, v37
	v_exp_f32_e32 v151, v151
	v_exp_f32_e32 v153, v152
	v_mul_f32_e32 v152, 0xbfb8aa3b, v33
	v_exp_f32_e32 v154, v152
	v_add_f32_e32 v151, 1.0, v151
	v_mul_f32_e32 v155, 0xbfb8aa3b, v34
	v_mul_f32_e32 v156, 0xbfb8aa3b, v39
	v_mul_f32_e32 v150, 0xbfb8aa3b, v36
	v_rcp_f32_e32 v152, v151
	v_add_f32_e32 v151, 1.0, v153
	v_add_f32_e32 v153, 1.0, v154
	v_mul_f32_e32 v154, 0xbfb8aa3b, v38
	v_exp_f32_e32 v155, v155
	v_exp_f32_e32 v157, v156
	v_mul_f32_e32 v156, 0xbfb8aa3b, v35
	v_exp_f32_e32 v150, v150
	v_exp_f32_e32 v154, v154
	v_exp_f32_e32 v162, v156
	v_add_f32_e32 v155, 1.0, v155
	v_add_f32_e32 v150, 1.0, v150
	v_add_f32_e32 v154, 1.0, v154
	v_rcp_f32_e32 v156, v155
	v_add_f32_e32 v155, 1.0, v157
	v_add_f32_e32 v157, 1.0, v162
	v_rcp_f32_e32 v150, v150
	v_rcp_f32_e32 v151, v151
	v_rcp_f32_e32 v153, v153
	v_rcp_f32_e32 v154, v154
	v_rcp_f32_e32 v155, v155
	v_rcp_f32_e32 v157, v157
	s_mov_b64 s[0:1], 0

; __device__ __forceinline__ float sigm(float x) { return __builtin_amdgcn_rcpf(1.f + __expf(-x)); }
; __device__ __forceinline__ float silu(float x) { return x * __builtin_amdgcn_rcpf(1.f + __expf(-x)); }
; __device__ __forceinline__ u32x4 pack8(const f32x4 a, const f32x4 b) { u32x4 w; w.x = cvt_pk_bf16(a[0], a[1]); w.y = cvt_pk_bf16(a[2], a[3]); w.z = cvt_pk_bf16(b[0], b[1]); w.w = cvt_pk_bf16(b[2], b[3]); return w; }
;     __device__ __forceinline__ void operator()(const f32x4 (&acc)[2][2][4][2], const Unit& u, int wr, int wc, int fr, int fq) const {
;     ...
;                 for (int m = 0; m < 4; ++m) { bf16_t* rowp = base + (size_t)(row0 + ai * HALF + m * 16) * 1024;
; #pragma unroll
;                     for (int bj = 0; bj < 2; ++bj) { f32x4 v0 = acc[ai][bj][m][0], v1 = acc[ai][bj][m][1];
;                         if (act == 1) {
; #pragma unroll
;                             for (int j = 0; j < 4; ++j) { v0[j] = silu(v0[j]); v1[j] = silu(v1[j]); } }
;                         else if (act == 2) {
; #pragma unroll
;                             for (int j = 0; j < 4; ++j) { v0[j] = sigm(v0[j]); v1[j] = sigm(v1[j]); } }
;                         *(u32x4*)(rowp + bj * HALF) = pack8(v0, v1); } }
.LBB0_236:
	v_cvt_pk_bf16_f32 v150, v150, v151
	v_cvt_pk_bf16_f32 v151, v154, v155
	s_nop 0
	v_cvt_pk_bf16_f32 v152, v152, v153
	v_cvt_pk_bf16_f32 v153, v156, v157
	s_cmp_gt_i32 s11, 1
	s_mov_b64 s[0:1], -1
	global_store_dwordx4 v[148:149], v[150:153], off offset:256 nt
	s_cbranch_scc0 .LBB0_238
	v_mul_f32_e32 v148, 0xbfb8aa3b, v28
	v_exp_f32_e32 v148, v148
	v_mul_f32_e32 v149, 0xbfb8aa3b, v24
	v_exp_f32_e32 v149, v149
	v_mul_f32_e32 v151, 0xbfb8aa3b, v25
	v_add_f32_e32 v148, 1.0, v148
	v_rcp_f32_e32 v150, v148
	v_mul_f32_e32 v148, 0xbfb8aa3b, v29
	v_exp_f32_e32 v148, v148
	v_exp_f32_e32 v153, v151
	v_add_f32_e32 v149, 1.0, v149
	v_rcp_f32_e32 v152, v149
	v_add_f32_e32 v148, 1.0, v148
	v_mul_f32_e32 v149, 0xbfb8aa3b, v30
	v_rcp_f32_e32 v151, v148
	v_add_f32_e32 v148, 1.0, v153
	v_exp_f32_e32 v149, v149
	v_mul_f32_e32 v153, 0xbfb8aa3b, v26
	v_exp_f32_e32 v155, v153
	v_rcp_f32_e32 v153, v148
	v_add_f32_e32 v148, 1.0, v149
	v_mul_f32_e32 v149, 0xbfb8aa3b, v31
	v_rcp_f32_e32 v154, v148
	v_add_f32_e32 v148, 1.0, v155
	v_exp_f32_e32 v149, v149
	v_mul_f32_e32 v155, 0xbfb8aa3b, v27
	v_exp_f32_e32 v157, v155
	v_rcp_f32_e32 v156, v148
	v_add_f32_e32 v148, 1.0, v149
	v_rcp_f32_e32 v155, v148
	v_add_f32_e32 v148, 1.0, v157
	v_rcp_f32_e32 v157, v148
	s_mov_b64 s[0:1], 0

; __device__ __forceinline__ float sigm(float x) { return __builtin_amdgcn_rcpf(1.f + __expf(-x)); }
; __device__ __forceinline__ float silu(float x) { return x * __builtin_amdgcn_rcpf(1.f + __expf(-x)); }
; __device__ __forceinline__ u32x4 pack8(const f32x4 a, const f32x4 b) { u32x4 w; w.x = cvt_pk_bf16(a[0], a[1]); w.y = cvt_pk_bf16(a[2], a[3]); w.z = cvt_pk_bf16(b[0], b[1]); w.w = cvt_pk_bf16(b[2], b[3]); return w; }
;     __device__ __forceinline__ void operator()(const f32x4 (&acc)[2][2][4][2], const Unit& u, int wr, int wc, int fr, int fq) const {
;     ...
;                 for (int m = 0; m < 4; ++m) { bf16_t* rowp = base + (size_t)(row0 + ai * HALF + m * 16) * 1024;
; #pragma unroll
;                     for (int bj = 0; bj < 2; ++bj) { f32x4 v0 = acc[ai][bj][m][0], v1 = acc[ai][bj][m][1];
;                         if (act == 1) {
; #pragma unroll
;                             for (int j = 0; j < 4; ++j) { v0[j] = silu(v0[j]); v1[j] = silu(v1[j]); } }
;                         else if (act == 2) {
; #pragma unroll
;                             for (int j = 0; j < 4; ++j) { v0[j] = sigm(v0[j]); v1[j] = sigm(v1[j]); } }
;                         *(u32x4*)(rowp + bj * HALF) = pack8(v0, v1); } }
.LBB0_241:
	v_lshlrev_b64 v[148:149], 11, v[144:145]
	v_lshl_add_u64 v[162:163], v[146:147], 0, v[148:149]
	s_mov_b64 s[0:1], 0x50000
	v_cvt_pk_bf16_f32 v150, v150, v151
	v_cvt_pk_bf16_f32 v151, v154, v155
	v_add_co_u32_e32 v154, vcc, 0x50000, v162
	v_lshl_add_u64 v[148:149], v[162:163], 0, s[0:1]
	v_cvt_pk_bf16_f32 v152, v152, v153
	v_cvt_pk_bf16_f32 v153, v156, v157
	s_nop 0
	v_addc_co_u32_e32 v155, vcc, 0, v163, vcc
	s_cmp_gt_i32 s11, 1
	s_mov_b64 s[0:1], -1
	global_store_dwordx4 v[154:155], v[150:153], off nt
	s_cbranch_scc0 .LBB0_243
	s_nop 0
	v_mul_f32_e32 v151, 0xbfb8aa3b, v16
	v_mul_f32_e32 v152, 0xbfb8aa3b, v21
	v_exp_f32_e32 v151, v151
	v_exp_f32_e32 v153, v152
	v_mul_f32_e32 v152, 0xbfb8aa3b, v17
	v_exp_f32_e32 v154, v152
	v_add_f32_e32 v151, 1.0, v151
	v_mul_f32_e32 v155, 0xbfb8aa3b, v18
	v_mul_f32_e32 v156, 0xbfb8aa3b, v23
	v_mul_f32_e32 v150, 0xbfb8aa3b, v20
	v_rcp_f32_e32 v152, v151
	v_add_f32_e32 v151, 1.0, v153
	v_add_f32_e32 v153, 1.0, v154
	v_mul_f32_e32 v154, 0xbfb8aa3b, v22
	v_exp_f32_e32 v155, v155
	v_exp_f32_e32 v157, v156
	v_mul_f32_e32 v156, 0xbfb8aa3b, v19
	v_exp_f32_e32 v150, v150
	v_exp_f32_e32 v154, v154
	v_exp_f32_e32 v162, v156
	v_add_f32_e32 v155, 1.0, v155
	v_add_f32_e32 v150, 1.0, v150
	v_add_f32_e32 v154, 1.0, v154
	v_rcp_f32_e32 v156, v155
	v_add_f32_e32 v155, 1.0, v157
	v_add_f32_e32 v157, 1.0, v162
	v_rcp_f32_e32 v150, v150
	v_rcp_f32_e32 v151, v151
	v_rcp_f32_e32 v153, v153
	v_rcp_f32_e32 v154, v154
	v_rcp_f32_e32 v155, v155
	v_rcp_f32_e32 v157, v157
	s_mov_b64 s[0:1], 0

; __device__ __forceinline__ float sigm(float x) { return __builtin_amdgcn_rcpf(1.f + __expf(-x)); }
; __device__ __forceinline__ float silu(float x) { return x * __builtin_amdgcn_rcpf(1.f + __expf(-x)); }
; __device__ __forceinline__ u32x4 pack8(const f32x4 a, const f32x4 b) { u32x4 w; w.x = cvt_pk_bf16(a[0], a[1]); w.y = cvt_pk_bf16(a[2], a[3]); w.z = cvt_pk_bf16(b[0], b[1]); w.w = cvt_pk_bf16(b[2], b[3]); return w; }
;     __device__ __forceinline__ void operator()(const f32x4 (&acc)[2][2][4][2], const Unit& u, int wr, int wc, int fr, int fq) const {
;     ...
;                 for (int m = 0; m < 4; ++m) { bf16_t* rowp = base + (size_t)(row0 + ai * HALF + m * 16) * 1024;
; #pragma unroll
;                     for (int bj = 0; bj < 2; ++bj) { f32x4 v0 = acc[ai][bj][m][0], v1 = acc[ai][bj][m][1];
;                         if (act == 1) {
; #pragma unroll
;                             for (int j = 0; j < 4; ++j) { v0[j] = silu(v0[j]); v1[j] = silu(v1[j]); } }
;                         else if (act == 2) {
; #pragma unroll
;                             for (int j = 0; j < 4; ++j) { v0[j] = sigm(v0[j]); v1[j] = sigm(v1[j]); } }
;                         *(u32x4*)(rowp + bj * HALF) = pack8(v0, v1); } }
.LBB0_246:
	v_cvt_pk_bf16_f32 v150, v150, v151
	v_cvt_pk_bf16_f32 v151, v154, v155
	s_nop 0
	v_cvt_pk_bf16_f32 v152, v152, v153
	v_cvt_pk_bf16_f32 v153, v156, v157
	s_cmp_gt_i32 s11, 1
	s_mov_b64 s[0:1], -1
	global_store_dwordx4 v[148:149], v[150:153], off offset:256 nt
	s_cbranch_scc0 .LBB0_248
	v_mul_f32_e32 v149, 0xbfb8aa3b, v8
	v_mul_f32_e32 v150, 0xbfb8aa3b, v13
	v_exp_f32_e32 v149, v149
	v_exp_f32_e32 v151, v150
	v_mul_f32_e32 v150, 0xbfb8aa3b, v9
	v_exp_f32_e32 v152, v150
	v_add_f32_e32 v149, 1.0, v149
	v_mul_f32_e32 v153, 0xbfb8aa3b, v10
	v_mul_f32_e32 v154, 0xbfb8aa3b, v15
	v_mul_f32_e32 v148, 0xbfb8aa3b, v12
	v_rcp_f32_e32 v150, v149
	v_add_f32_e32 v149, 1.0, v151
	v_add_f32_e32 v151, 1.0, v152
	v_mul_f32_e32 v152, 0xbfb8aa3b, v14
	v_exp_f32_e32 v153, v153
	v_exp_f32_e32 v155, v154
	v_mul_f32_e32 v154, 0xbfb8aa3b, v11
	v_exp_f32_e32 v148, v148
	v_exp_f32_e32 v152, v152
	v_exp_f32_e32 v156, v154
	v_add_f32_e32 v153, 1.0, v153
	v_add_f32_e32 v148, 1.0, v148
	v_add_f32_e32 v152, 1.0, v152
	v_rcp_f32_e32 v154, v153
	v_add_f32_e32 v153, 1.0, v155
	v_add_f32_e32 v155, 1.0, v156
	v_rcp_f32_e32 v148, v148
	v_rcp_f32_e32 v149, v149
	v_rcp_f32_e32 v151, v151
	v_rcp_f32_e32 v152, v152
	v_rcp_f32_e32 v153, v153
	v_rcp_f32_e32 v155, v155
	s_mov_b64 s[0:1], 0

; __device__ __forceinline__ float sigm(float x) { return __builtin_amdgcn_rcpf(1.f + __expf(-x)); }
; __device__ __forceinline__ float silu(float x) { return x * __builtin_amdgcn_rcpf(1.f + __expf(-x)); }
; __device__ __forceinline__ u32x4 pack8(const f32x4 a, const f32x4 b) { u32x4 w; w.x = cvt_pk_bf16(a[0], a[1]); w.y = cvt_pk_bf16(a[2], a[3]); w.z = cvt_pk_bf16(b[0], b[1]); w.w = cvt_pk_bf16(b[2], b[3]); return w; }
;     __device__ __forceinline__ void operator()(const f32x4 (&acc)[2][2][4][2], const Unit& u, int wr, int wc, int fr, int fq) const {
;     ...
;                 for (int m = 0; m < 4; ++m) { bf16_t* rowp = base + (size_t)(row0 + ai * HALF + m * 16) * 1024;
; #pragma unroll
;                     for (int bj = 0; bj < 2; ++bj) { f32x4 v0 = acc[ai][bj][m][0], v1 = acc[ai][bj][m][1];
;                         if (act == 1) {
; #pragma unroll
;                             for (int j = 0; j < 4; ++j) { v0[j] = silu(v0[j]); v1[j] = silu(v1[j]); } }
;                         else if (act == 2) {
; #pragma unroll
;                             for (int j = 0; j < 4; ++j) { v0[j] = sigm(v0[j]); v1[j] = sigm(v1[j]); } }
;                         *(u32x4*)(rowp + bj * HALF) = pack8(v0, v1); } }
.LBB0_251:
	v_lshlrev_b64 v[156:157], 11, v[144:145]
	v_lshl_add_u64 v[156:157], v[146:147], 0, v[156:157]
	s_mov_b64 s[0:1], 0x58000
	v_cvt_pk_bf16_f32 v148, v148, v149
	v_cvt_pk_bf16_f32 v149, v152, v153
	v_add_co_u32_e32 v152, vcc, 0x58000, v156
	v_lshl_add_u64 v[146:147], v[156:157], 0, s[0:1]
	v_cvt_pk_bf16_f32 v150, v150, v151
	v_cvt_pk_bf16_f32 v151, v154, v155
	s_nop 0
	v_addc_co_u32_e32 v153, vcc, 0, v157, vcc
	s_cmp_gt_i32 s11, 1
	s_mov_b64 s[0:1], -1
	global_store_dwordx4 v[152:153], v[148:151], off nt
	s_cbranch_scc0 .LBB0_253
	v_mul_f32_e32 v145, 0xbfb8aa3b, v4
	v_exp_f32_e32 v145, v145
	v_mul_f32_e32 v148, 0xbfb8aa3b, v0
	v_exp_f32_e32 v148, v148
	v_mul_f32_e32 v150, 0xbfb8aa3b, v1
	v_add_f32_e32 v145, 1.0, v145
	v_exp_f32_e32 v151, v150
	v_add_f32_e32 v149, 1.0, v148
	v_rcp_f32_e32 v148, v145
	v_mul_f32_e32 v145, 0xbfb8aa3b, v5
	v_exp_f32_e32 v145, v145
	v_rcp_f32_e32 v150, v149
	v_mul_f32_e32 v154, 0xbfb8aa3b, v3
	v_exp_f32_e32 v155, v154
	v_add_f32_e32 v145, 1.0, v145
	v_rcp_f32_e32 v149, v145
	v_add_f32_e32 v145, 1.0, v151
	v_mul_f32_e32 v151, 0xbfb8aa3b, v6
	v_exp_f32_e32 v152, v151
	v_mul_f32_e32 v151, 0xbfb8aa3b, v2
	v_exp_f32_e32 v153, v151
	v_rcp_f32_e32 v151, v145
	v_add_f32_e32 v145, 1.0, v152
	v_rcp_f32_e32 v152, v145
	v_add_f32_e32 v145, 1.0, v153
	v_mul_f32_e32 v153, 0xbfb8aa3b, v7
	v_exp_f32_e32 v153, v153
	v_rcp_f32_e32 v154, v145
	s_mov_b64 s[0:1], 0
	v_add_f32_e32 v145, 1.0, v153
	v_rcp_f32_e32 v153, v145
	v_add_f32_e32 v145, 1.0, v155
	v_rcp_f32_e32 v155, v145

; __device__ __forceinline__ float sigm(float x) { return __builtin_amdgcn_rcpf(1.f + __expf(-x)); }
; __device__ __forceinline__ float silu(float x) { return x * __builtin_amdgcn_rcpf(1.f + __expf(-x)); }
; __device__ __forceinline__ u32x4 pack8(const f32x4 a, const f32x4 b) { u32x4 w; w.x = cvt_pk_bf16(a[0], a[1]); w.y = cvt_pk_bf16(a[2], a[3]); w.z = cvt_pk_bf16(b[0], b[1]); w.w = cvt_pk_bf16(b[2], b[3]); return w; }
;     __device__ __forceinline__ void operator()(const f32x4 (&acc)[2][2][4][2], const Unit& u, int wr, int wc, int fr, int fq) const {
;     ...
;         } else if (pn >= 20 && pn < 28) {
;             bf16_t* base = P + 5 * bstride + (pn - 20) * 128 + wc * 32 + 8 * fq;
; #pragma unroll
;             for (int ai = 0; ai < 2; ++ai)
; #pragma unroll
;                 for (int m = 0; m < 4; ++m) { bf16_t* rowp = base + (size_t)(row0 + ai * HALF + m * 16) * 1024;
;                     const f32x4 v0 = acc[ai][0][m][0] * acc[ai][1][m][0], v1 = acc[ai][0][m][1] * acc[ai][1][m][1];
;                     *(u32x4*)rowp = pack8(v0, v1); }
;     ...
;                     for (int bj = 0; bj < 2; ++bj) { f32x4 v0 = acc[ai][bj][m][0], v1 = acc[ai][bj][m][1];
;                         if (act == 1) {
; #pragma unroll
;                             for (int j = 0; j < 4; ++j) { v0[j] = silu(v0[j]); v1[j] = silu(v1[j]); } }
;                         else if (act == 2) {
; #pragma unroll
;                             for (int j = 0; j < 4; ++j) { v0[j] = sigm(v0[j]); v1[j] = sigm(v1[j]); } }
;                         *(u32x4*)(rowp + bj * HALF) = pack8(v0, v1); } }
.LBB0_256:
	v_cvt_pk_bf16_f32 v148, v148, v149
	v_cvt_pk_bf16_f32 v149, v152, v153
	s_nop 0
	v_cvt_pk_bf16_f32 v150, v150, v151
	v_cvt_pk_bf16_f32 v151, v154, v155
	global_store_dwordx4 v[146:147], v[148:151], off offset:256 nt
	s_mov_b64 s[0:1], 0
.LBB0_257:
	s_and_b64 vcc, exec, s[0:1]
	s_cbranch_vccz .LBB0_259
	s_lshl_b32 s0, s37, 8
	v_readlane_b32 s1, v254, 19
	s_add_u32 s0, s1, s0
	v_readlane_b32 s1, v254, 20
	s_addc_u32 s1, s1, 0
	s_lshl_b32 s11, s29, 1
	s_add_u32 s0, s0, s11
	s_addc_u32 s1, s1, 0
	v_lshlrev_b32_e32 v146, 1, v136
	v_mov_b32_e32 v147, v189
	v_lshl_add_u64 v[146:147], s[0:1], 0, v[146:147]
	s_mov_b64 s[0:1], 0xac7ec00
	v_ashrrev_i32_e32 v145, 31, v144
	v_lshl_add_u64 v[152:153], v[146:147], 0, s[0:1]
	v_lshlrev_b64 v[146:147], 11, v[144:145]
	v_pk_mul_f32 v[148:149], v[124:125], v[116:117]
	v_lshl_add_u64 v[146:147], v[152:153], 0, v[146:147]
	v_pk_mul_f32 v[150:151], v[126:127], v[118:119]
	v_cvt_pk_bf16_f32 v148, v148, v149
	v_pk_mul_f32 v[154:155], v[122:123], v[114:115]
	v_pk_mul_f32 v[156:157], v[120:121], v[112:113]
	v_cvt_pk_bf16_f32 v149, v150, v151
	v_pk_mul_f32 v[162:163], v[104:105], v[96:97]
	v_cvt_pk_bf16_f32 v150, v156, v157
	v_cvt_pk_bf16_f32 v151, v154, v155
	global_store_dwordx4 v[146:147], v[148:151], off nt
	v_pk_mul_f32 v[156:157], v[106:107], v[98:99]
	s_mov_b32 s0, 0x40000
	v_or_b32_e32 v148, 16, v144
	v_ashrrev_i32_e32 v149, 31, v148
	v_lshlrev_b64 v[148:149], 11, v[148:149]
	v_lshl_add_u64 v[154:155], v[152:153], 0, v[148:149]
	v_pk_mul_f32 v[148:149], v[108:109], v[100:101]
	v_pk_mul_f32 v[150:151], v[110:111], v[102:103]
	v_cvt_pk_bf16_f32 v148, v148, v149
	s_nop 0
	v_cvt_pk_bf16_f32 v149, v150, v151
	v_cvt_pk_bf16_f32 v150, v162, v163
	v_cvt_pk_bf16_f32 v151, v156, v157
	global_store_dwordx4 v[154:155], v[148:151], off nt
	v_pk_mul_f32 v[156:157], v[90:91], v[82:83]
	v_pk_mul_f32 v[162:163], v[88:89], v[80:81]
	v_or_b32_e32 v148, 32, v144
	v_ashrrev_i32_e32 v149, 31, v148
	v_lshlrev_b64 v[148:149], 11, v[148:149]
	v_lshl_add_u64 v[154:155], v[152:153], 0, v[148:149]
	v_pk_mul_f32 v[148:149], v[92:93], v[84:85]
	v_pk_mul_f32 v[150:151], v[94:95], v[86:87]
	v_cvt_pk_bf16_f32 v148, v148, v149
	s_nop 0
	v_cvt_pk_bf16_f32 v149, v150, v151
	v_cvt_pk_bf16_f32 v150, v162, v163
	v_cvt_pk_bf16_f32 v151, v156, v157
	global_store_dwordx4 v[154:155], v[148:151], off nt
	v_pk_mul_f32 v[154:155], v[74:75], v[66:67]
	v_pk_mul_f32 v[156:157], v[72:73], v[64:65]
	v_or_b32_e32 v148, 48, v144
	v_ashrrev_i32_e32 v149, 31, v148
	v_lshlrev_b64 v[148:149], 11, v[148:149]
	v_lshl_add_u64 v[152:153], v[152:153], 0, v[148:149]
	v_pk_mul_f32 v[150:151], v[78:79], v[70:71]
	v_pk_mul_f32 v[148:149], v[76:77], v[68:69]
	s_nop 0
	v_cvt_pk_bf16_f32 v148, v148, v149
	v_cvt_pk_bf16_f32 v149, v150, v151
	v_cvt_pk_bf16_f32 v150, v156, v157
	v_cvt_pk_bf16_f32 v151, v154, v155
	global_store_dwordx4 v[152:153], v[148:151], off nt
	v_pk_mul_f32 v[152:153], v[58:59], v[50:51]
	v_pk_mul_f32 v[154:155], v[56:57], v[48:49]
	v_pk_mul_f32 v[150:151], v[62:63], v[54:55]
	v_pk_mul_f32 v[148:149], v[60:61], v[52:53]
	s_nop 0
	v_cvt_pk_bf16_f32 v148, v148, v149
	v_cvt_pk_bf16_f32 v149, v150, v151
	v_cvt_pk_bf16_f32 v150, v154, v155
	v_cvt_pk_bf16_f32 v151, v152, v153
	v_add_co_u32_e32 v152, vcc, s0, v146
	s_mov_b32 s0, 0x48000
	s_nop 0
	v_addc_co_u32_e32 v153, vcc, 0, v147, vcc
	global_store_dwordx4 v[152:153], v[148:151], off nt
	v_pk_mul_f32 v[152:153], v[42:43], v[34:35]
	v_pk_mul_f32 v[154:155], v[40:41], v[32:33]
	v_pk_mul_f32 v[150:151], v[46:47], v[38:39]
	v_pk_mul_f32 v[148:149], v[44:45], v[36:37]
	s_nop 0
	v_cvt_pk_bf16_f32 v148, v148, v149
	v_cvt_pk_bf16_f32 v149, v150, v151
	v_cvt_pk_bf16_f32 v150, v154, v155
	v_cvt_pk_bf16_f32 v151, v152, v153
	v_add_co_u32_e32 v152, vcc, s0, v146
	s_mov_b32 s0, 0x50000
	s_nop 0
	v_addc_co_u32_e32 v153, vcc, 0, v147, vcc
	global_store_dwordx4 v[152:153], v[148:151], off nt
	v_pk_mul_f32 v[152:153], v[26:27], v[18:19]
	v_pk_mul_f32 v[154:155], v[24:25], v[16:17]
	v_pk_mul_f32 v[150:151], v[30:31], v[22:23]
	v_pk_mul_f32 v[148:149], v[28:29], v[20:21]
	s_nop 0
	v_cvt_pk_bf16_f32 v148, v148, v149
	v_cvt_pk_bf16_f32 v149, v150, v151
	v_cvt_pk_bf16_f32 v150, v154, v155
	v_cvt_pk_bf16_f32 v151, v152, v153
	v_add_co_u32_e32 v152, vcc, s0, v146
	v_pk_mul_f32 v[154:155], v[8:9], v[0:1]
	s_nop 0
	v_addc_co_u32_e32 v153, vcc, 0, v147, vcc
	v_add_co_u32_e32 v146, vcc, 0x58000, v146
	global_store_dwordx4 v[152:153], v[148:151], off nt
	s_nop 0
	v_addc_co_u32_e32 v147, vcc, 0, v147, vcc
	v_pk_mul_f32 v[150:151], v[14:15], v[6:7]
	v_pk_mul_f32 v[148:149], v[12:13], v[4:5]
	v_pk_mul_f32 v[152:153], v[10:11], v[2:3]
	v_cvt_pk_bf16_f32 v148, v148, v149
	v_cvt_pk_bf16_f32 v149, v150, v151
	v_cvt_pk_bf16_f32 v150, v154, v155
	s_nop 0
	v_cvt_pk_bf16_f32 v151, v152, v153
	global_store_dwordx4 v[146:147], v[148:151], off nt

; __device__ __forceinline__ u32x4 pack8(const f32x4 a, const f32x4 b) { u32x4 w; w.x = cvt_pk_bf16(a[0], a[1]); w.y = cvt_pk_bf16(a[2], a[3]); w.z = cvt_pk_bf16(b[0], b[1]); w.w = cvt_pk_bf16(b[2], b[3]); return w; }
;     __device__ __forceinline__ void operator()(const f32x4 (&acc)[2][2][4][2], const Unit& u, int wr, int wc, int fr, int fq) const {
;     ...
;             for (int m = 0; m < 4; ++m) { const size_t off = (size_t)(row0 + ai * HALF + m * 16) * 1024 + col0;
; #pragma unroll
;                 for (int bj = 0; bj < 2; ++bj) { const u32x4 gw = *(const u32x4*)(Gt + off + bj * HALF);
;                     f32x4 v0 = acc[ai][bj][m][0], v1 = acc[ai][bj][m][1];
;                     v0[0] *= bflo(gw.x); v0[1] *= bfhi(gw.x); v0[2] *= bflo(gw.y); v0[3] *= bfhi(gw.y);
;                     v1[0] *= bflo(gw.z); v1[1] *= bfhi(gw.z); v1[2] *= bflo(gw.w); v1[3] *= bfhi(gw.w);
;                     if (ADD) { const u32x4 pw = *(const u32x4*)(MG + off + bj * HALF);
;                         v0[0] += bflo(pw.x); v0[1] += bfhi(pw.x); v0[2] += bflo(pw.y); v0[3] += bfhi(pw.y);
;                         v1[0] += bflo(pw.z); v1[1] += bfhi(pw.z); v1[2] += bflo(pw.w); v1[3] += bfhi(pw.w); }
;                     *(u32x4*)(MG + off + bj * HALF) = pack8(v0, v1); }
;                 asm volatile("" ::: "memory"); }
.LBB0_728:
	s_mov_b64 s[18:19], s[16:17]
	s_mov_b64 s[38:39], s[14:15]
	s_waitcnt vmcnt(14)
	v_lshlrev_b32_e32 v145, 16, v140
	v_lshlrev_b32_e32 v149, 16, v150
	v_and_b32_e32 v140, 0xffff0000, v140
	v_and_b32_e32 v150, 0xffff0000, v150
	v_fmac_f32_e32 v149, v124, v145
	v_fmac_f32_e32 v150, v125, v140
	v_cvt_pk_bf16_f32 v140, v149, v150
	v_lshlrev_b32_e32 v145, 16, v141
	v_lshlrev_b32_e32 v149, 16, v151
	v_and_b32_e32 v141, 0xffff0000, v141
	v_and_b32_e32 v151, 0xffff0000, v151
	v_fmac_f32_e32 v149, v126, v145
	v_fmac_f32_e32 v151, v127, v141
	v_cvt_pk_bf16_f32 v141, v149, v151
	v_lshlrev_b32_e32 v145, 16, v142
	v_lshlrev_b32_e32 v149, 16, v152
	v_and_b32_e32 v142, 0xffff0000, v142
	v_and_b32_e32 v152, 0xffff0000, v152
	v_fmac_f32_e32 v149, v120, v145
	v_fmac_f32_e32 v152, v121, v142
	v_cvt_pk_bf16_f32 v142, v149, v152
	v_lshlrev_b32_e32 v145, 16, v143
	v_lshlrev_b32_e32 v149, 16, v153
	v_and_b32_e32 v143, 0xffff0000, v143
	v_and_b32_e32 v153, 0xffff0000, v153
	v_fmac_f32_e32 v149, v122, v145
	v_fmac_f32_e32 v153, v123, v143
	v_cvt_pk_bf16_f32 v143, v149, v153
	global_store_dwordx4 v144, v[140:143], s[38:39] nt
	v_add_u32_e32 v145, 0x40000, v144
	global_load_dwordx4 v[150:153], v145, s[38:39]
	global_load_dwordx4 v[140:143], v145, s[18:19]
	s_waitcnt vmcnt(15)
	v_lshlrev_b32_e32 v145, 16, v154
	v_lshlrev_b32_e32 v149, 16, v158
	v_and_b32_e32 v154, 0xffff0000, v154
	v_and_b32_e32 v158, 0xffff0000, v158
	v_fmac_f32_e32 v149, v116, v145
	v_fmac_f32_e32 v158, v117, v154
	v_cvt_pk_bf16_f32 v154, v149, v158
	v_lshlrev_b32_e32 v145, 16, v155
	v_lshlrev_b32_e32 v149, 16, v159
	v_and_b32_e32 v155, 0xffff0000, v155
	v_and_b32_e32 v159, 0xffff0000, v159
	v_fmac_f32_e32 v149, v118, v145
	v_fmac_f32_e32 v159, v119, v155
	v_cvt_pk_bf16_f32 v155, v149, v159
	v_lshlrev_b32_e32 v145, 16, v156
	v_lshlrev_b32_e32 v149, 16, v160
	v_and_b32_e32 v156, 0xffff0000, v156
	v_and_b32_e32 v160, 0xffff0000, v160
	v_fmac_f32_e32 v149, v112, v145
	v_fmac_f32_e32 v160, v113, v156
	v_cvt_pk_bf16_f32 v156, v149, v160
	v_lshlrev_b32_e32 v145, 16, v157
	v_lshlrev_b32_e32 v149, 16, v161
	v_and_b32_e32 v157, 0xffff0000, v157
	v_and_b32_e32 v161, 0xffff0000, v161
	v_fmac_f32_e32 v149, v114, v145
	v_fmac_f32_e32 v161, v115, v157
	v_cvt_pk_bf16_f32 v157, v149, v161
	global_store_dwordx4 v144, v[154:157], s[38:39] offset:256 nt
	v_add_u32_e32 v145, 0x40000, v144
	global_load_dwordx4 v[158:161], v145, s[38:39] offset:256
	global_load_dwordx4 v[154:157], v145, s[18:19] offset:256
	s_add_u32 s18, s16, 0x8000
	s_addc_u32 s19, s17, 0
	s_add_u32 s38, s14, 0x8000
	s_addc_u32 s39, s15, 0
	s_waitcnt vmcnt(16)
	v_lshlrev_b32_e32 v145, 16, v162
	v_lshlrev_b32_e32 v149, 16, v166
	v_and_b32_e32 v162, 0xffff0000, v162
	v_and_b32_e32 v166, 0xffff0000, v166
	v_fmac_f32_e32 v149, v108, v145
	v_fmac_f32_e32 v166, v109, v162
	v_cvt_pk_bf16_f32 v162, v149, v166
	v_lshlrev_b32_e32 v145, 16, v163
	v_lshlrev_b32_e32 v149, 16, v167
	v_and_b32_e32 v163, 0xffff0000, v163
	v_and_b32_e32 v167, 0xffff0000, v167
	v_fmac_f32_e32 v149, v110, v145
	v_fmac_f32_e32 v167, v111, v163
	v_cvt_pk_bf16_f32 v163, v149, v167
	v_lshlrev_b32_e32 v145, 16, v164
	v_lshlrev_b32_e32 v149, 16, v168
	v_and_b32_e32 v164, 0xffff0000, v164
	v_and_b32_e32 v168, 0xffff0000, v168
	v_fmac_f32_e32 v149, v104, v145
	v_fmac_f32_e32 v168, v105, v164
	v_cvt_pk_bf16_f32 v164, v149, v168
	v_lshlrev_b32_e32 v145, 16, v165
	v_lshlrev_b32_e32 v149, 16, v169
	v_and_b32_e32 v165, 0xffff0000, v165
	v_and_b32_e32 v169, 0xffff0000, v169
	v_fmac_f32_e32 v149, v106, v145
	v_fmac_f32_e32 v169, v107, v165
	v_cvt_pk_bf16_f32 v165, v149, v169
	global_store_dwordx4 v144, v[162:165], s[38:39] nt
	v_add_u32_e32 v145, 0x40000, v144
	global_load_dwordx4 v[166:169], v145, s[38:39]
	global_load_dwordx4 v[162:165], v145, s[18:19]
	s_waitcnt vmcnt(17)
	v_lshlrev_b32_e32 v145, 16, v170
	v_lshlrev_b32_e32 v149, 16, v174
	v_and_b32_e32 v170, 0xffff0000, v170
	v_and_b32_e32 v174, 0xffff0000, v174
	v_fmac_f32_e32 v149, v100, v145
	v_fmac_f32_e32 v174, v101, v170
	v_cvt_pk_bf16_f32 v170, v149, v174
	v_lshlrev_b32_e32 v145, 16, v171
	v_lshlrev_b32_e32 v149, 16, v175
	v_and_b32_e32 v171, 0xffff0000, v171
	v_and_b32_e32 v175, 0xffff0000, v175
	v_fmac_f32_e32 v149, v102, v145
	v_fmac_f32_e32 v175, v103, v171
	v_cvt_pk_bf16_f32 v171, v149, v175
	v_lshlrev_b32_e32 v145, 16, v172
	v_lshlrev_b32_e32 v149, 16, v176
	v_and_b32_e32 v172, 0xffff0000, v172
	v_and_b32_e32 v176, 0xffff0000, v176
	v_fmac_f32_e32 v149, v96, v145
	v_fmac_f32_e32 v176, v97, v172
	v_cvt_pk_bf16_f32 v172, v149, v176
	v_lshlrev_b32_e32 v145, 16, v173
	v_lshlrev_b32_e32 v149, 16, v177
	v_and_b32_e32 v173, 0xffff0000, v173
	v_and_b32_e32 v177, 0xffff0000, v177
	v_fmac_f32_e32 v149, v98, v145
	v_fmac_f32_e32 v177, v99, v173
	v_cvt_pk_bf16_f32 v173, v149, v177
	global_store_dwordx4 v144, v[170:173], s[38:39] offset:256 nt
	v_add_u32_e32 v145, 0x40000, v144
	global_load_dwordx4 v[174:177], v145, s[38:39] offset:256
	global_load_dwordx4 v[170:173], v145, s[18:19] offset:256
	s_add_u32 s18, s16, 0x10000
	s_addc_u32 s19, s17, 0
	s_add_u32 s38, s14, 0x10000
	s_addc_u32 s39, s15, 0
	s_waitcnt vmcnt(18)
; __device__ __forceinline__ u32x4 pack8(const f32x4 a, const f32x4 b) { u32x4 w; w.x = cvt_pk_bf16(a[0], a[1]); w.y = cvt_pk_bf16(a[2], a[3]); w.z = cvt_pk_bf16(b[0], b[1]); w.w = cvt_pk_bf16(b[2], b[3]); return w; }
;     __device__ __forceinline__ void operator()(const f32x4 (&acc)[2][2][4][2], const Unit& u, int wr, int wc, int fr, int fq) const {
;     ...
;             for (int m = 0; m < 4; ++m) { const size_t off = (size_t)(row0 + ai * HALF + m * 16) * 1024 + col0;
; #pragma unroll
;                 for (int bj = 0; bj < 2; ++bj) { const u32x4 gw = *(const u32x4*)(Gt + off + bj * HALF);
;                     f32x4 v0 = acc[ai][bj][m][0], v1 = acc[ai][bj][m][1];
;                     v0[0] *= bflo(gw.x); v0[1] *= bfhi(gw.x); v0[2] *= bflo(gw.y); v0[3] *= bfhi(gw.y);
;                     v1[0] *= bflo(gw.z); v1[1] *= bfhi(gw.z); v1[2] *= bflo(gw.w); v1[3] *= bfhi(gw.w);
;                     if (ADD) { const u32x4 pw = *(const u32x4*)(MG + off + bj * HALF);
;                         v0[0] += bflo(pw.x); v0[1] += bfhi(pw.x); v0[2] += bflo(pw.y); v0[3] += bfhi(pw.y);
;                         v1[0] += bflo(pw.z); v1[1] += bfhi(pw.z); v1[2] += bflo(pw.w); v1[3] += bfhi(pw.w); }
;                     *(u32x4*)(MG + off + bj * HALF) = pack8(v0, v1); }
;                 asm volatile("" ::: "memory"); }
	v_lshlrev_b32_e32 v145, 16, v178
	v_lshlrev_b32_e32 v149, 16, v182
	v_and_b32_e32 v178, 0xffff0000, v178
	v_and_b32_e32 v182, 0xffff0000, v182
	v_fmac_f32_e32 v149, v92, v145
	v_fmac_f32_e32 v182, v93, v178
	v_cvt_pk_bf16_f32 v178, v149, v182
	v_lshlrev_b32_e32 v145, 16, v179
	v_lshlrev_b32_e32 v149, 16, v183
	v_and_b32_e32 v179, 0xffff0000, v179
	v_and_b32_e32 v183, 0xffff0000, v183
	v_fmac_f32_e32 v149, v94, v145
	v_fmac_f32_e32 v183, v95, v179
	v_cvt_pk_bf16_f32 v179, v149, v183
	v_lshlrev_b32_e32 v145, 16, v180
	v_lshlrev_b32_e32 v149, 16, v184
	v_and_b32_e32 v180, 0xffff0000, v180
	v_and_b32_e32 v184, 0xffff0000, v184
	v_fmac_f32_e32 v149, v88, v145
	v_fmac_f32_e32 v184, v89, v180
	v_cvt_pk_bf16_f32 v180, v149, v184
	v_lshlrev_b32_e32 v145, 16, v181
	v_lshlrev_b32_e32 v149, 16, v185
	v_and_b32_e32 v181, 0xffff0000, v181
	v_and_b32_e32 v185, 0xffff0000, v185
	v_fmac_f32_e32 v149, v90, v145
	v_fmac_f32_e32 v185, v91, v181
	v_cvt_pk_bf16_f32 v181, v149, v185
	global_store_dwordx4 v144, v[178:181], s[38:39] nt
	v_add_u32_e32 v145, 0x40000, v144
	global_load_dwordx4 v[182:185], v145, s[38:39]
	global_load_dwordx4 v[178:181], v145, s[18:19]
	s_waitcnt vmcnt(19)
	v_lshlrev_b32_e32 v145, 16, v194
	v_lshlrev_b32_e32 v149, 16, v198
	v_and_b32_e32 v194, 0xffff0000, v194
	v_and_b32_e32 v198, 0xffff0000, v198
	v_fmac_f32_e32 v149, v84, v145
	v_fmac_f32_e32 v198, v85, v194
	v_cvt_pk_bf16_f32 v194, v149, v198
	v_lshlrev_b32_e32 v145, 16, v195
	v_lshlrev_b32_e32 v149, 16, v199
	v_and_b32_e32 v195, 0xffff0000, v195
	v_and_b32_e32 v199, 0xffff0000, v199
	v_fmac_f32_e32 v149, v86, v145
	v_fmac_f32_e32 v199, v87, v195
	v_cvt_pk_bf16_f32 v195, v149, v199
	v_lshlrev_b32_e32 v145, 16, v196
	v_lshlrev_b32_e32 v149, 16, v200
	v_and_b32_e32 v196, 0xffff0000, v196
	v_and_b32_e32 v200, 0xffff0000, v200
	v_fmac_f32_e32 v149, v80, v145
	v_fmac_f32_e32 v200, v81, v196
	v_cvt_pk_bf16_f32 v196, v149, v200
	v_lshlrev_b32_e32 v145, 16, v197
	v_lshlrev_b32_e32 v149, 16, v201
	v_and_b32_e32 v197, 0xffff0000, v197
	v_and_b32_e32 v201, 0xffff0000, v201
	v_fmac_f32_e32 v149, v82, v145
	v_fmac_f32_e32 v201, v83, v197
	v_cvt_pk_bf16_f32 v197, v149, v201
	global_store_dwordx4 v144, v[194:197], s[38:39] offset:256 nt
	v_add_u32_e32 v145, 0x40000, v144
	global_load_dwordx4 v[198:201], v145, s[38:39] offset:256
	global_load_dwordx4 v[194:197], v145, s[18:19] offset:256
	s_add_u32 s18, s16, 0x18000
	s_addc_u32 s19, s17, 0
	s_add_u32 s38, s14, 0x18000
	s_addc_u32 s39, s15, 0
	s_waitcnt vmcnt(20)
	v_lshlrev_b32_e32 v145, 16, v202
	v_lshlrev_b32_e32 v149, 16, v210
	v_and_b32_e32 v202, 0xffff0000, v202
	v_and_b32_e32 v210, 0xffff0000, v210
	v_fmac_f32_e32 v149, v76, v145
	v_fmac_f32_e32 v210, v77, v202
	v_cvt_pk_bf16_f32 v202, v149, v210
	v_lshlrev_b32_e32 v145, 16, v203
	v_lshlrev_b32_e32 v149, 16, v211
	v_and_b32_e32 v203, 0xffff0000, v203
	v_and_b32_e32 v211, 0xffff0000, v211
	v_fmac_f32_e32 v149, v78, v145
	v_fmac_f32_e32 v211, v79, v203
	v_cvt_pk_bf16_f32 v203, v149, v211
	v_lshlrev_b32_e32 v145, 16, v204
	v_lshlrev_b32_e32 v149, 16, v212
	v_and_b32_e32 v204, 0xffff0000, v204
	v_and_b32_e32 v212, 0xffff0000, v212
	v_fmac_f32_e32 v149, v72, v145
	v_fmac_f32_e32 v212, v73, v204
	v_cvt_pk_bf16_f32 v204, v149, v212
	v_lshlrev_b32_e32 v145, 16, v205
	v_lshlrev_b32_e32 v149, 16, v213
	v_and_b32_e32 v205, 0xffff0000, v205
	v_and_b32_e32 v213, 0xffff0000, v213
	v_fmac_f32_e32 v149, v74, v145
	v_fmac_f32_e32 v213, v75, v205
	v_cvt_pk_bf16_f32 v205, v149, v213
	global_store_dwordx4 v144, v[202:205], s[38:39] nt
	v_add_u32_e32 v145, 0x40000, v144
	global_load_dwordx4 v[210:213], v145, s[38:39]
	global_load_dwordx4 v[202:205], v145, s[18:19]
	s_waitcnt vmcnt(21)
	v_lshlrev_b32_e32 v145, 16, v214
	v_lshlrev_b32_e32 v149, 16, v218
	v_and_b32_e32 v214, 0xffff0000, v214
	v_and_b32_e32 v218, 0xffff0000, v218
	v_fmac_f32_e32 v149, v68, v145
	v_fmac_f32_e32 v218, v69, v214
	v_cvt_pk_bf16_f32 v214, v149, v218
	v_lshlrev_b32_e32 v145, 16, v215
	v_lshlrev_b32_e32 v149, 16, v219
	v_and_b32_e32 v215, 0xffff0000, v215
	v_and_b32_e32 v219, 0xffff0000, v219
	v_fmac_f32_e32 v149, v70, v145
	v_fmac_f32_e32 v219, v71, v215
	v_cvt_pk_bf16_f32 v215, v149, v219
	v_lshlrev_b32_e32 v145, 16, v216
	v_lshlrev_b32_e32 v149, 16, v220
	v_and_b32_e32 v216, 0xffff0000, v216
	v_and_b32_e32 v220, 0xffff0000, v220
	v_fmac_f32_e32 v149, v64, v145
	v_fmac_f32_e32 v220, v65, v216
	v_cvt_pk_bf16_f32 v216, v149, v220
	v_lshlrev_b32_e32 v145, 16, v217
	v_lshlrev_b32_e32 v149, 16, v221
	v_and_b32_e32 v217, 0xffff0000, v217
	v_and_b32_e32 v221, 0xffff0000, v221
	v_fmac_f32_e32 v149, v66, v145
	v_fmac_f32_e32 v221, v67, v217
	v_cvt_pk_bf16_f32 v217, v149, v221
	global_store_dwordx4 v144, v[214:217], s[38:39] offset:256 nt
	v_add_u32_e32 v145, 0x40000, v144
	global_load_dwordx4 v[218:221], v145, s[38:39] offset:256
	global_load_dwordx4 v[214:217], v145, s[18:19] offset:256
	s_mov_b64 s[18:19], s[16:17]
	s_mov_b64 s[38:39], s[14:15]
	s_waitcnt vmcnt(21)
	v_lshlrev_b32_e32 v145, 16, v140
	v_lshlrev_b32_e32 v149, 16, v150
	v_and_b32_e32 v140, 0xffff0000, v140
	v_and_b32_e32 v150, 0xffff0000, v150
	v_fmac_f32_e32 v149, v60, v145
	v_fmac_f32_e32 v150, v61, v140
	v_cvt_pk_bf16_f32 v140, v149, v150
	v_lshlrev_b32_e32 v145, 16, v141
	v_lshlrev_b32_e32 v149, 16, v151
	v_and_b32_e32 v141, 0xffff0000, v141
	v_and_b32_e32 v151, 0xffff0000, v151
	v_fmac_f32_e32 v149, v62, v145
	v_fmac_f32_e32 v151, v63, v141
	v_cvt_pk_bf16_f32 v141, v149, v151
	v_lshlrev_b32_e32 v145, 16, v142
	v_lshlrev_b32_e32 v149, 16, v152
	v_and_b32_e32 v142, 0xffff0000, v142
	v_and_b32_e32 v152, 0xffff0000, v152
	v_fmac_f32_e32 v149, v56, v145
	v_fmac_f32_e32 v152, v57, v142
	v_cvt_pk_bf16_f32 v142, v149, v152
	v_lshlrev_b32_e32 v145, 16, v143
	v_lshlrev_b32_e32 v149, 16, v153
	v_and_b32_e32 v143, 0xffff0000, v143
	v_and_b32_e32 v153, 0xffff0000, v153
	v_fmac_f32_e32 v149, v58, v145
	v_fmac_f32_e32 v153, v59, v143
	v_cvt_pk_bf16_f32 v143, v149, v153
	v_add_u32_e32 v145, 0x40000, v144
	global_store_dwordx4 v145, v[140:143], s[38:39] nt
	s_waitcnt vmcnt(19)
; __device__ __forceinline__ u32x4 pack8(const f32x4 a, const f32x4 b) { u32x4 w; w.x = cvt_pk_bf16(a[0], a[1]); w.y = cvt_pk_bf16(a[2], a[3]); w.z = cvt_pk_bf16(b[0], b[1]); w.w = cvt_pk_bf16(b[2], b[3]); return w; }
;     __device__ __forceinline__ void operator()(const f32x4 (&acc)[2][2][4][2], const Unit& u, int wr, int wc, int fr, int fq) const {
;     ...
;             for (int m = 0; m < 4; ++m) { const size_t off = (size_t)(row0 + ai * HALF + m * 16) * 1024 + col0;
; #pragma unroll
;                 for (int bj = 0; bj < 2; ++bj) { const u32x4 gw = *(const u32x4*)(Gt + off + bj * HALF);
;                     f32x4 v0 = acc[ai][bj][m][0], v1 = acc[ai][bj][m][1];
;                     v0[0] *= bflo(gw.x); v0[1] *= bfhi(gw.x); v0[2] *= bflo(gw.y); v0[3] *= bfhi(gw.y);
;                     v1[0] *= bflo(gw.z); v1[1] *= bfhi(gw.z); v1[2] *= bflo(gw.w); v1[3] *= bfhi(gw.w);
;                     if (ADD) { const u32x4 pw = *(const u32x4*)(MG + off + bj * HALF);
;                         v0[0] += bflo(pw.x); v0[1] += bfhi(pw.x); v0[2] += bflo(pw.y); v0[3] += bfhi(pw.y);
;                         v1[0] += bflo(pw.z); v1[1] += bfhi(pw.z); v1[2] += bflo(pw.w); v1[3] += bfhi(pw.w); }
;                     *(u32x4*)(MG + off + bj * HALF) = pack8(v0, v1); }
;                 asm volatile("" ::: "memory"); }
	v_lshlrev_b32_e32 v145, 16, v154
	v_lshlrev_b32_e32 v149, 16, v158
	v_and_b32_e32 v154, 0xffff0000, v154
	v_and_b32_e32 v158, 0xffff0000, v158
	v_fmac_f32_e32 v149, v52, v145
	v_fmac_f32_e32 v158, v53, v154
	v_cvt_pk_bf16_f32 v154, v149, v158
	v_lshlrev_b32_e32 v145, 16, v155
	v_lshlrev_b32_e32 v149, 16, v159
	v_and_b32_e32 v155, 0xffff0000, v155
	v_and_b32_e32 v159, 0xffff0000, v159
	v_fmac_f32_e32 v149, v54, v145
	v_fmac_f32_e32 v159, v55, v155
	v_cvt_pk_bf16_f32 v155, v149, v159
	v_lshlrev_b32_e32 v145, 16, v156
	v_lshlrev_b32_e32 v149, 16, v160
	v_and_b32_e32 v156, 0xffff0000, v156
	v_and_b32_e32 v160, 0xffff0000, v160
	v_fmac_f32_e32 v149, v48, v145
	v_fmac_f32_e32 v160, v49, v156
	v_cvt_pk_bf16_f32 v156, v149, v160
	v_lshlrev_b32_e32 v145, 16, v157
	v_lshlrev_b32_e32 v149, 16, v161
	v_and_b32_e32 v157, 0xffff0000, v157
	v_and_b32_e32 v161, 0xffff0000, v161
	v_fmac_f32_e32 v149, v50, v145
	v_fmac_f32_e32 v161, v51, v157
	v_cvt_pk_bf16_f32 v157, v149, v161
	v_add_u32_e32 v145, 0x40000, v144
	global_store_dwordx4 v145, v[154:157], s[38:39] offset:256 nt
	s_add_u32 s18, s16, 0x8000
	s_addc_u32 s19, s17, 0
	s_add_u32 s38, s14, 0x8000
	s_addc_u32 s39, s15, 0
	s_waitcnt vmcnt(17)
	v_lshlrev_b32_e32 v145, 16, v162
	v_lshlrev_b32_e32 v149, 16, v166
	v_and_b32_e32 v162, 0xffff0000, v162
	v_and_b32_e32 v166, 0xffff0000, v166
	v_fmac_f32_e32 v149, v44, v145
	v_fmac_f32_e32 v166, v45, v162
	v_cvt_pk_bf16_f32 v162, v149, v166
	v_lshlrev_b32_e32 v145, 16, v163
	v_lshlrev_b32_e32 v149, 16, v167
	v_and_b32_e32 v163, 0xffff0000, v163
	v_and_b32_e32 v167, 0xffff0000, v167
	v_fmac_f32_e32 v149, v46, v145
	v_fmac_f32_e32 v167, v47, v163
	v_cvt_pk_bf16_f32 v163, v149, v167
	v_lshlrev_b32_e32 v145, 16, v164
	v_lshlrev_b32_e32 v149, 16, v168
	v_and_b32_e32 v164, 0xffff0000, v164
	v_and_b32_e32 v168, 0xffff0000, v168
	v_fmac_f32_e32 v149, v40, v145
	v_fmac_f32_e32 v168, v41, v164
	v_cvt_pk_bf16_f32 v164, v149, v168
	v_lshlrev_b32_e32 v145, 16, v165
	v_lshlrev_b32_e32 v149, 16, v169
	v_and_b32_e32 v165, 0xffff0000, v165
	v_and_b32_e32 v169, 0xffff0000, v169
	v_fmac_f32_e32 v149, v42, v145
	v_fmac_f32_e32 v169, v43, v165
	v_cvt_pk_bf16_f32 v165, v149, v169
	v_add_u32_e32 v145, 0x40000, v144
	global_store_dwordx4 v145, v[162:165], s[38:39] nt
	s_waitcnt vmcnt(15)
	v_lshlrev_b32_e32 v145, 16, v170
	v_lshlrev_b32_e32 v149, 16, v174
	v_and_b32_e32 v170, 0xffff0000, v170
	v_and_b32_e32 v174, 0xffff0000, v174
	v_fmac_f32_e32 v149, v36, v145
	v_fmac_f32_e32 v174, v37, v170
	v_cvt_pk_bf16_f32 v170, v149, v174
	v_lshlrev_b32_e32 v145, 16, v171
	v_lshlrev_b32_e32 v149, 16, v175
	v_and_b32_e32 v171, 0xffff0000, v171
	v_and_b32_e32 v175, 0xffff0000, v175
	v_fmac_f32_e32 v149, v38, v145
	v_fmac_f32_e32 v175, v39, v171
	v_cvt_pk_bf16_f32 v171, v149, v175
	v_lshlrev_b32_e32 v145, 16, v172
	v_lshlrev_b32_e32 v149, 16, v176
	v_and_b32_e32 v172, 0xffff0000, v172
	v_and_b32_e32 v176, 0xffff0000, v176
	v_fmac_f32_e32 v149, v32, v145
	v_fmac_f32_e32 v176, v33, v172
	v_cvt_pk_bf16_f32 v172, v149, v176
	v_lshlrev_b32_e32 v145, 16, v173
	v_lshlrev_b32_e32 v149, 16, v177
	v_and_b32_e32 v173, 0xffff0000, v173
	v_and_b32_e32 v177, 0xffff0000, v177
	v_fmac_f32_e32 v149, v34, v145
	v_fmac_f32_e32 v177, v35, v173
	v_cvt_pk_bf16_f32 v173, v149, v177
	v_add_u32_e32 v145, 0x40000, v144
	global_store_dwordx4 v145, v[170:173], s[38:39] offset:256 nt
	s_add_u32 s18, s16, 0x10000
	s_addc_u32 s19, s17, 0
	s_add_u32 s38, s14, 0x10000
	s_addc_u32 s39, s15, 0
	s_waitcnt vmcnt(13)
; __device__ __forceinline__ u32x4 pack8(const f32x4 a, const f32x4 b) { u32x4 w; w.x = cvt_pk_bf16(a[0], a[1]); w.y = cvt_pk_bf16(a[2], a[3]); w.z = cvt_pk_bf16(b[0], b[1]); w.w = cvt_pk_bf16(b[2], b[3]); return w; }
;     __device__ __forceinline__ void operator()(const f32x4 (&acc)[2][2][4][2], const Unit& u, int wr, int wc, int fr, int fq) const {
;     ...
;             for (int m = 0; m < 4; ++m) { const size_t off = (size_t)(row0 + ai * HALF + m * 16) * 1024 + col0;
; #pragma unroll
;                 for (int bj = 0; bj < 2; ++bj) { const u32x4 gw = *(const u32x4*)(Gt + off + bj * HALF);
;                     f32x4 v0 = acc[ai][bj][m][0], v1 = acc[ai][bj][m][1];
;                     v0[0] *= bflo(gw.x); v0[1] *= bfhi(gw.x); v0[2] *= bflo(gw.y); v0[3] *= bfhi(gw.y);
;                     v1[0] *= bflo(gw.z); v1[1] *= bfhi(gw.z); v1[2] *= bflo(gw.w); v1[3] *= bfhi(gw.w);
;                     if (ADD) { const u32x4 pw = *(const u32x4*)(MG + off + bj * HALF);
;                         v0[0] += bflo(pw.x); v0[1] += bfhi(pw.x); v0[2] += bflo(pw.y); v0[3] += bfhi(pw.y);
;                         v1[0] += bflo(pw.z); v1[1] += bfhi(pw.z); v1[2] += bflo(pw.w); v1[3] += bfhi(pw.w); }
;                     *(u32x4*)(MG + off + bj * HALF) = pack8(v0, v1); }
;                 asm volatile("" ::: "memory"); }
	v_lshlrev_b32_e32 v145, 16, v178
	v_lshlrev_b32_e32 v149, 16, v182
	v_and_b32_e32 v178, 0xffff0000, v178
	v_and_b32_e32 v182, 0xffff0000, v182
	v_fmac_f32_e32 v149, v28, v145
	v_fmac_f32_e32 v182, v29, v178
	v_cvt_pk_bf16_f32 v178, v149, v182
	v_lshlrev_b32_e32 v145, 16, v179
	v_lshlrev_b32_e32 v149, 16, v183
	v_and_b32_e32 v179, 0xffff0000, v179
	v_and_b32_e32 v183, 0xffff0000, v183
	v_fmac_f32_e32 v149, v30, v145
	v_fmac_f32_e32 v183, v31, v179
	v_cvt_pk_bf16_f32 v179, v149, v183
	v_lshlrev_b32_e32 v145, 16, v180
	v_lshlrev_b32_e32 v149, 16, v184
	v_and_b32_e32 v180, 0xffff0000, v180
	v_and_b32_e32 v184, 0xffff0000, v184
	v_fmac_f32_e32 v149, v24, v145
	v_fmac_f32_e32 v184, v25, v180
	v_cvt_pk_bf16_f32 v180, v149, v184
	v_lshlrev_b32_e32 v145, 16, v181
	v_lshlrev_b32_e32 v149, 16, v185
	v_and_b32_e32 v181, 0xffff0000, v181
	v_and_b32_e32 v185, 0xffff0000, v185
	v_fmac_f32_e32 v149, v26, v145
	v_fmac_f32_e32 v185, v27, v181
	v_cvt_pk_bf16_f32 v181, v149, v185
	v_add_u32_e32 v145, 0x40000, v144
	global_store_dwordx4 v145, v[178:181], s[38:39] nt
	s_waitcnt vmcnt(11)
	v_lshlrev_b32_e32 v145, 16, v194
	v_lshlrev_b32_e32 v149, 16, v198
	v_and_b32_e32 v194, 0xffff0000, v194
	v_and_b32_e32 v198, 0xffff0000, v198
	v_fmac_f32_e32 v149, v20, v145
	v_fmac_f32_e32 v198, v21, v194
	v_cvt_pk_bf16_f32 v194, v149, v198
	v_lshlrev_b32_e32 v145, 16, v195
	v_lshlrev_b32_e32 v149, 16, v199
	v_and_b32_e32 v195, 0xffff0000, v195
	v_and_b32_e32 v199, 0xffff0000, v199
	v_fmac_f32_e32 v149, v22, v145
	v_fmac_f32_e32 v199, v23, v195
	v_cvt_pk_bf16_f32 v195, v149, v199
	v_lshlrev_b32_e32 v145, 16, v196
	v_lshlrev_b32_e32 v149, 16, v200
	v_and_b32_e32 v196, 0xffff0000, v196
	v_and_b32_e32 v200, 0xffff0000, v200
	v_fmac_f32_e32 v149, v16, v145
	v_fmac_f32_e32 v200, v17, v196
	v_cvt_pk_bf16_f32 v196, v149, v200
	v_lshlrev_b32_e32 v145, 16, v197
	v_lshlrev_b32_e32 v149, 16, v201
	v_and_b32_e32 v197, 0xffff0000, v197
	v_and_b32_e32 v201, 0xffff0000, v201
	v_fmac_f32_e32 v149, v18, v145
	v_fmac_f32_e32 v201, v19, v197
	v_cvt_pk_bf16_f32 v197, v149, v201
	v_add_u32_e32 v145, 0x40000, v144
	global_store_dwordx4 v145, v[194:197], s[38:39] offset:256 nt
	s_add_u32 s18, s16, 0x18000
	s_addc_u32 s19, s17, 0
	s_add_u32 s38, s14, 0x18000
	s_addc_u32 s39, s15, 0
	s_waitcnt vmcnt(9)
	v_lshlrev_b32_e32 v145, 16, v202
	v_lshlrev_b32_e32 v149, 16, v210
	v_and_b32_e32 v202, 0xffff0000, v202
	v_and_b32_e32 v210, 0xffff0000, v210
	v_fmac_f32_e32 v149, v12, v145
	v_fmac_f32_e32 v210, v13, v202
	v_cvt_pk_bf16_f32 v202, v149, v210
	v_lshlrev_b32_e32 v145, 16, v203
	v_lshlrev_b32_e32 v149, 16, v211
	v_and_b32_e32 v203, 0xffff0000, v203
	v_and_b32_e32 v211, 0xffff0000, v211
	v_fmac_f32_e32 v149, v14, v145
	v_fmac_f32_e32 v211, v15, v203
	v_cvt_pk_bf16_f32 v203, v149, v211
	v_lshlrev_b32_e32 v145, 16, v204
	v_lshlrev_b32_e32 v149, 16, v212
	v_and_b32_e32 v204, 0xffff0000, v204
	v_and_b32_e32 v212, 0xffff0000, v212
	v_fmac_f32_e32 v149, v8, v145
	v_fmac_f32_e32 v212, v9, v204
	v_cvt_pk_bf16_f32 v204, v149, v212
	v_lshlrev_b32_e32 v145, 16, v205
	v_lshlrev_b32_e32 v149, 16, v213
	v_and_b32_e32 v205, 0xffff0000, v205
	v_and_b32_e32 v213, 0xffff0000, v213
	v_fmac_f32_e32 v149, v10, v145
	v_fmac_f32_e32 v213, v11, v205
	v_cvt_pk_bf16_f32 v205, v149, v213
	v_add_u32_e32 v145, 0x40000, v144
	global_store_dwordx4 v145, v[202:205], s[38:39] nt
	s_waitcnt vmcnt(7)
	v_lshlrev_b32_e32 v145, 16, v214
	v_lshlrev_b32_e32 v149, 16, v218
	v_and_b32_e32 v214, 0xffff0000, v214
	v_and_b32_e32 v218, 0xffff0000, v218
	v_fmac_f32_e32 v149, v4, v145
	v_fmac_f32_e32 v218, v5, v214
	v_cvt_pk_bf16_f32 v214, v149, v218
	v_lshlrev_b32_e32 v145, 16, v215
	v_lshlrev_b32_e32 v149, 16, v219
	v_and_b32_e32 v215, 0xffff0000, v215
	v_and_b32_e32 v219, 0xffff0000, v219
	v_fmac_f32_e32 v149, v6, v145
	v_fmac_f32_e32 v219, v7, v215
	v_cvt_pk_bf16_f32 v215, v149, v219
	v_lshlrev_b32_e32 v145, 16, v216
	v_lshlrev_b32_e32 v149, 16, v220
	v_and_b32_e32 v216, 0xffff0000, v216
	v_and_b32_e32 v220, 0xffff0000, v220
	v_fmac_f32_e32 v149, v0, v145
	v_fmac_f32_e32 v220, v1, v216
	v_cvt_pk_bf16_f32 v216, v149, v220
	v_lshlrev_b32_e32 v145, 16, v217
	v_lshlrev_b32_e32 v149, 16, v221
	v_and_b32_e32 v217, 0xffff0000, v217
	v_and_b32_e32 v221, 0xffff0000, v221
	v_fmac_f32_e32 v149, v2, v145
	v_fmac_f32_e32 v221, v3, v217
	v_cvt_pk_bf16_f32 v217, v149, v221
	v_add_u32_e32 v145, 0x40000, v144
	global_store_dwordx4 v145, v[214:217], s[38:39] offset:256 nt

; __device__ __forceinline__ float silu(float x) { return x * __builtin_amdgcn_rcpf(1.f + __expf(-x)); }
; __device__ __forceinline__ u32x4 pack8(const f32x4 a, const f32x4 b) { u32x4 w; w.x = cvt_pk_bf16(a[0], a[1]); w.y = cvt_pk_bf16(a[2], a[3]); w.z = cvt_pk_bf16(b[0], b[1]); w.w = cvt_pk_bf16(b[2], b[3]); return w; }
;     __device__ __forceinline__ void operator()(const f32x4 (&acc)[2][2][4][2], const Unit& u, int wr, int wc, int fr, int fq) const {
;         const int row0 = u.pm * BM + wr * 64 + fr; bf16_t* base = O + u.pn * 128 + wc * 32 + 8 * fq;
; #pragma unroll
;         for (int ai = 0; ai < 2; ++ai)
; #pragma unroll
;             for (int m = 0; m < 4; ++m) { bf16_t* rowp = base + (size_t)(row0 + ai * HALF + m * 16) * ldc; f32x4 v0, v1;
; #pragma unroll
;                 for (int j = 0; j < 4; ++j) { v0[j] = silu(acc[ai][0][m][0][j]) * acc[ai][1][m][0][j]; v1[j] = silu(acc[ai][0][m][1][j]) * acc[ai][1][m][1][j]; }
;                 *(u32x4*)rowp = pack8(v0, v1); }
;     }
.LBB0_1123:
	v_mul_f32_e32 v147, 0xbfb8aa3b, v124
	v_exp_f32_e32 v147, v147
	v_lshl_add_u32 v146, s16, 8, v143
	s_lshl_b32 s16, s17, 7
	s_ashr_i32 s17, s16, 31
	v_add_f32_e32 v147, 1.0, v147
	v_rcp_f32_e32 v147, v147
	v_lshl_add_u64 v[140:141], s[16:17], 1, v[134:135]
	s_movk_i32 s9, 0x1600
	s_andn2_b64 vcc, exec, s[6:7]
	v_mul_f32_e32 v124, v124, v147
	v_mul_f32_e32 v120, v124, v120
	v_mul_f32_e32 v124, 0xbfb8aa3b, v116
	v_exp_f32_e32 v124, v124
	s_nop 0
	v_add_f32_e32 v124, 1.0, v124
	v_rcp_f32_e32 v124, v124
	s_nop 0
	v_mul_f32_e32 v116, v116, v124
	v_mul_f32_e32 v124, v116, v112
	v_mul_f32_e32 v112, 0xbfb8aa3b, v125
	v_mul_f32_e32 v116, 0xbfb8aa3b, v117
	v_exp_f32_e32 v112, v112
	v_exp_f32_e32 v116, v116
	v_add_f32_e32 v112, 1.0, v112
	v_add_f32_e32 v116, 1.0, v116
	v_rcp_f32_e32 v112, v112
	v_rcp_f32_e32 v116, v116
	v_mul_f32_e32 v112, v125, v112
	v_mul_f32_e32 v116, v117, v116
	v_mul_f32_e32 v112, v112, v121
	v_mul_f32_e32 v121, v116, v113
	v_mul_f32_e32 v116, 0xbfb8aa3b, v118
	v_exp_f32_e32 v116, v116
	v_mul_f32_e32 v113, 0xbfb8aa3b, v126
	v_exp_f32_e32 v113, v113
	v_cvt_pk_bf16_f32 v112, v120, v112
	v_add_f32_e32 v116, 1.0, v116
	v_rcp_f32_e32 v116, v116
	v_add_f32_e32 v113, 1.0, v113
	v_rcp_f32_e32 v113, v113
	v_mul_f32_e32 v116, v118, v116
	v_mul_f32_e32 v118, v116, v114
	v_mul_f32_e32 v114, 0xbfb8aa3b, v127
	v_mul_f32_e32 v116, 0xbfb8aa3b, v119
	v_exp_f32_e32 v114, v114
	v_exp_f32_e32 v116, v116
	v_mul_f32_e32 v113, v126, v113
	v_mul_f32_e32 v113, v113, v122
	v_add_f32_e32 v114, 1.0, v114
	v_add_f32_e32 v116, 1.0, v116
	v_rcp_f32_e32 v114, v114
	v_rcp_f32_e32 v116, v116
	v_mul_f32_e32 v114, v127, v114
	v_mul_f32_e32 v116, v119, v116
	v_mul_f32_e32 v114, v114, v123
	v_mul_f32_e32 v115, v116, v115
	v_mad_i64_i32 v[116:117], s[16:17], v146, s9, v[140:141]
	v_cvt_pk_bf16_f32 v113, v113, v114
	v_cvt_pk_bf16_f32 v114, v124, v121
	v_cvt_pk_bf16_f32 v115, v118, v115
	global_store_dwordx4 v[116:117], v[112:115], off nt
	s_nop 1
	v_mul_f32_e32 v113, 0xbfb8aa3b, v108
	v_exp_f32_e32 v113, v113
	v_or_b32_e32 v112, 16, v146
	v_add_f32_e32 v113, 1.0, v113
	v_rcp_f32_e32 v113, v113
	s_nop 0
	v_mul_f32_e32 v108, v108, v113
	v_mul_f32_e32 v104, v108, v104
	v_mul_f32_e32 v108, 0xbfb8aa3b, v100
	v_exp_f32_e32 v108, v108
	s_nop 0
	v_add_f32_e32 v108, 1.0, v108
	v_rcp_f32_e32 v108, v108
	s_nop 0
	v_mul_f32_e32 v100, v100, v108
	v_mul_f32_e32 v108, v100, v96
	v_mul_f32_e32 v96, 0xbfb8aa3b, v109
	v_mul_f32_e32 v100, 0xbfb8aa3b, v101
	v_exp_f32_e32 v96, v96
	v_exp_f32_e32 v100, v100
	v_add_f32_e32 v96, 1.0, v96
	v_add_f32_e32 v100, 1.0, v100
	v_rcp_f32_e32 v96, v96
	v_rcp_f32_e32 v100, v100
	v_mul_f32_e32 v96, v109, v96
	v_mul_f32_e32 v100, v101, v100
	v_mul_f32_e32 v96, v96, v105
	v_mul_f32_e32 v105, v100, v97
	v_mul_f32_e32 v100, 0xbfb8aa3b, v102
	v_exp_f32_e32 v100, v100
	v_mul_f32_e32 v97, 0xbfb8aa3b, v110
	v_exp_f32_e32 v97, v97
	v_cvt_pk_bf16_f32 v96, v104, v96
	v_add_f32_e32 v100, 1.0, v100
	v_rcp_f32_e32 v100, v100
	v_add_f32_e32 v97, 1.0, v97
	v_rcp_f32_e32 v97, v97
	v_mul_f32_e32 v100, v102, v100
	v_mul_f32_e32 v102, v100, v98
	v_mul_f32_e32 v98, 0xbfb8aa3b, v111
	v_mul_f32_e32 v100, 0xbfb8aa3b, v103
	v_exp_f32_e32 v98, v98
	v_exp_f32_e32 v100, v100
	v_mul_f32_e32 v97, v110, v97
	v_mul_f32_e32 v97, v97, v106
	v_add_f32_e32 v98, 1.0, v98
	v_add_f32_e32 v100, 1.0, v100
	v_rcp_f32_e32 v98, v98
	v_rcp_f32_e32 v100, v100
	v_mul_f32_e32 v98, v111, v98
	v_mul_f32_e32 v100, v103, v100
	v_mul_f32_e32 v98, v98, v107
	v_mul_f32_e32 v99, v100, v99
	v_mad_i64_i32 v[100:101], s[16:17], v112, s9, v[140:141]
	v_cvt_pk_bf16_f32 v97, v97, v98
	v_cvt_pk_bf16_f32 v98, v108, v105
	v_cvt_pk_bf16_f32 v99, v102, v99
	global_store_dwordx4 v[100:101], v[96:99], off nt
	s_nop 1
	v_mul_f32_e32 v97, 0xbfb8aa3b, v92
	v_exp_f32_e32 v97, v97
	v_or_b32_e32 v96, 32, v146
	v_add_f32_e32 v97, 1.0, v97
	v_rcp_f32_e32 v97, v97
	s_nop 0
	v_mul_f32_e32 v92, v92, v97
	v_mul_f32_e32 v88, v92, v88
	v_mul_f32_e32 v92, 0xbfb8aa3b, v84
	v_exp_f32_e32 v92, v92
	s_nop 0
	v_add_f32_e32 v92, 1.0, v92
	v_rcp_f32_e32 v92, v92
	s_nop 0
	v_mul_f32_e32 v84, v84, v92
	v_mul_f32_e32 v92, v84, v80
	v_mul_f32_e32 v80, 0xbfb8aa3b, v93
	v_mul_f32_e32 v84, 0xbfb8aa3b, v85
	v_exp_f32_e32 v80, v80
	v_exp_f32_e32 v84, v84
	v_add_f32_e32 v80, 1.0, v80
	v_add_f32_e32 v84, 1.0, v84
	v_rcp_f32_e32 v80, v80
	v_rcp_f32_e32 v84, v84
	v_mul_f32_e32 v80, v93, v80
	v_mul_f32_e32 v84, v85, v84
	v_mul_f32_e32 v80, v80, v89
	v_mul_f32_e32 v89, v84, v81
	v_mul_f32_e32 v84, 0xbfb8aa3b, v86
	v_exp_f32_e32 v84, v84
	v_mul_f32_e32 v81, 0xbfb8aa3b, v94
	v_exp_f32_e32 v81, v81
	v_cvt_pk_bf16_f32 v80, v88, v80
	v_add_f32_e32 v84, 1.0, v84
	v_rcp_f32_e32 v84, v84
	v_add_f32_e32 v81, 1.0, v81
	v_rcp_f32_e32 v81, v81
	v_mul_f32_e32 v84, v86, v84
	v_mul_f32_e32 v86, v84, v82
	v_mul_f32_e32 v82, 0xbfb8aa3b, v95
	v_mul_f32_e32 v84, 0xbfb8aa3b, v87
	v_exp_f32_e32 v82, v82
	v_exp_f32_e32 v84, v84
	v_mul_f32_e32 v81, v94, v81
	v_mul_f32_e32 v81, v81, v90
	v_add_f32_e32 v82, 1.0, v82
	v_add_f32_e32 v84, 1.0, v84
	v_rcp_f32_e32 v82, v82
	v_rcp_f32_e32 v84, v84
	v_mul_f32_e32 v82, v95, v82
	v_mul_f32_e32 v84, v87, v84
	v_mul_f32_e32 v82, v82, v91
	v_mul_f32_e32 v83, v84, v83
	v_mad_i64_i32 v[84:85], s[16:17], v96, s9, v[140:141]
	v_cvt_pk_bf16_f32 v81, v81, v82
	v_cvt_pk_bf16_f32 v82, v92, v89
	v_cvt_pk_bf16_f32 v83, v86, v83
	global_store_dwordx4 v[84:85], v[80:83], off nt
	s_nop 1
	v_mul_f32_e32 v81, 0xbfb8aa3b, v76
	v_exp_f32_e32 v81, v81
	v_or_b32_e32 v80, 48, v146
	v_add_f32_e32 v81, 1.0, v81
	v_rcp_f32_e32 v81, v81
	s_nop 0
	v_mul_f32_e32 v76, v76, v81
	v_mul_f32_e32 v72, v76, v72
	v_mul_f32_e32 v76, 0xbfb8aa3b, v68
; __device__ __forceinline__ float silu(float x) { return x * __builtin_amdgcn_rcpf(1.f + __expf(-x)); }
; __device__ __forceinline__ u32x4 pack8(const f32x4 a, const f32x4 b) { u32x4 w; w.x = cvt_pk_bf16(a[0], a[1]); w.y = cvt_pk_bf16(a[2], a[3]); w.z = cvt_pk_bf16(b[0], b[1]); w.w = cvt_pk_bf16(b[2], b[3]); return w; }
;     __device__ __forceinline__ void operator()(const f32x4 (&acc)[2][2][4][2], const Unit& u, int wr, int wc, int fr, int fq) const {
;         const int row0 = u.pm * BM + wr * 64 + fr; bf16_t* base = O + u.pn * 128 + wc * 32 + 8 * fq;
; #pragma unroll
;         for (int ai = 0; ai < 2; ++ai)
; #pragma unroll
;             for (int m = 0; m < 4; ++m) { bf16_t* rowp = base + (size_t)(row0 + ai * HALF + m * 16) * ldc; f32x4 v0, v1;
; #pragma unroll
;                 for (int j = 0; j < 4; ++j) { v0[j] = silu(acc[ai][0][m][0][j]) * acc[ai][1][m][0][j]; v1[j] = silu(acc[ai][0][m][1][j]) * acc[ai][1][m][1][j]; }
;                 *(u32x4*)rowp = pack8(v0, v1); }
;     }
	v_exp_f32_e32 v76, v76
	s_nop 0
	v_add_f32_e32 v76, 1.0, v76
	v_rcp_f32_e32 v76, v76
	s_nop 0
	v_mul_f32_e32 v68, v68, v76
	v_mul_f32_e32 v76, v68, v64
	v_mul_f32_e32 v64, 0xbfb8aa3b, v77
	v_mul_f32_e32 v68, 0xbfb8aa3b, v69
	v_exp_f32_e32 v64, v64
	v_exp_f32_e32 v68, v68
	v_add_f32_e32 v64, 1.0, v64
	v_add_f32_e32 v68, 1.0, v68
	v_rcp_f32_e32 v64, v64
	v_rcp_f32_e32 v68, v68
	v_mul_f32_e32 v64, v77, v64
	v_mul_f32_e32 v68, v69, v68
	v_mul_f32_e32 v64, v64, v73
	v_mul_f32_e32 v73, v68, v65
	v_mul_f32_e32 v68, 0xbfb8aa3b, v70
	v_exp_f32_e32 v68, v68
	v_mul_f32_e32 v65, 0xbfb8aa3b, v78
	v_exp_f32_e32 v65, v65
	v_cvt_pk_bf16_f32 v64, v72, v64
	v_add_f32_e32 v68, 1.0, v68
	v_rcp_f32_e32 v68, v68
	v_add_f32_e32 v65, 1.0, v65
	v_rcp_f32_e32 v65, v65
	v_mul_f32_e32 v68, v70, v68
	v_mul_f32_e32 v70, v68, v66
	v_mul_f32_e32 v66, 0xbfb8aa3b, v79
	v_mul_f32_e32 v68, 0xbfb8aa3b, v71
	v_exp_f32_e32 v66, v66
	v_exp_f32_e32 v68, v68
	v_mul_f32_e32 v65, v78, v65
	v_mul_f32_e32 v65, v65, v74
	v_add_f32_e32 v66, 1.0, v66
	v_add_f32_e32 v68, 1.0, v68
	v_rcp_f32_e32 v66, v66
	v_rcp_f32_e32 v68, v68
	v_mul_f32_e32 v66, v79, v66
	v_mul_f32_e32 v68, v71, v68
	v_mul_f32_e32 v66, v66, v75
	v_mul_f32_e32 v67, v68, v67
	v_mad_i64_i32 v[68:69], s[16:17], v80, s9, v[140:141]
	v_cvt_pk_bf16_f32 v65, v65, v66
	v_cvt_pk_bf16_f32 v66, v76, v73
	v_cvt_pk_bf16_f32 v67, v70, v67
	global_store_dwordx4 v[68:69], v[64:67], off nt
	s_nop 1
	v_mul_f32_e32 v65, 0xbfb8aa3b, v60
	v_exp_f32_e32 v65, v65
	v_add_u32_e32 v64, 0x80, v146
	v_add_f32_e32 v65, 1.0, v65
	v_rcp_f32_e32 v65, v65
	s_nop 0
	v_mul_f32_e32 v60, v60, v65
	v_mul_f32_e32 v56, v60, v56
	v_mul_f32_e32 v60, 0xbfb8aa3b, v52
	v_exp_f32_e32 v60, v60
	s_nop 0
	v_add_f32_e32 v60, 1.0, v60
	v_rcp_f32_e32 v60, v60
	s_nop 0
	v_mul_f32_e32 v52, v52, v60
	v_mul_f32_e32 v60, v52, v48
	v_mul_f32_e32 v48, 0xbfb8aa3b, v61
	v_mul_f32_e32 v52, 0xbfb8aa3b, v53
	v_exp_f32_e32 v48, v48
	v_exp_f32_e32 v52, v52
	v_add_f32_e32 v48, 1.0, v48
	v_add_f32_e32 v52, 1.0, v52
	v_rcp_f32_e32 v48, v48
	v_rcp_f32_e32 v52, v52
	v_mul_f32_e32 v48, v61, v48
	v_mul_f32_e32 v52, v53, v52
	v_mul_f32_e32 v48, v48, v57
	v_mul_f32_e32 v57, v52, v49
	v_mul_f32_e32 v52, 0xbfb8aa3b, v54
	v_exp_f32_e32 v52, v52
	v_mul_f32_e32 v49, 0xbfb8aa3b, v62
	v_exp_f32_e32 v49, v49
	v_cvt_pk_bf16_f32 v48, v56, v48
	v_add_f32_e32 v52, 1.0, v52
	v_rcp_f32_e32 v52, v52
	v_add_f32_e32 v49, 1.0, v49
	v_rcp_f32_e32 v49, v49
	v_mul_f32_e32 v52, v54, v52
	v_mul_f32_e32 v54, v52, v50
	v_mul_f32_e32 v50, 0xbfb8aa3b, v63
	v_mul_f32_e32 v52, 0xbfb8aa3b, v55
	v_exp_f32_e32 v50, v50
	v_exp_f32_e32 v52, v52
	v_mul_f32_e32 v49, v62, v49
	v_mul_f32_e32 v49, v49, v58
	v_add_f32_e32 v50, 1.0, v50
	v_add_f32_e32 v52, 1.0, v52
	v_rcp_f32_e32 v50, v50
	v_rcp_f32_e32 v52, v52
	v_mul_f32_e32 v50, v63, v50
	v_mul_f32_e32 v52, v55, v52
	v_mul_f32_e32 v50, v50, v59
	v_mul_f32_e32 v51, v52, v51
	v_mad_i64_i32 v[52:53], s[16:17], v64, s9, v[140:141]
	v_cvt_pk_bf16_f32 v49, v49, v50
	v_cvt_pk_bf16_f32 v50, v60, v57
	v_cvt_pk_bf16_f32 v51, v54, v51
	global_store_dwordx4 v[52:53], v[48:51], off nt
	s_nop 1
	v_mul_f32_e32 v49, 0xbfb8aa3b, v44
	v_exp_f32_e32 v49, v49
	v_add_u32_e32 v48, 0x90, v146
	v_add_f32_e32 v49, 1.0, v49
	v_rcp_f32_e32 v49, v49
	s_nop 0
	v_mul_f32_e32 v44, v44, v49
	v_mul_f32_e32 v40, v44, v40
	v_mul_f32_e32 v44, 0xbfb8aa3b, v36
	v_exp_f32_e32 v44, v44
	s_nop 0
	v_add_f32_e32 v44, 1.0, v44
	v_rcp_f32_e32 v44, v44
	s_nop 0
	v_mul_f32_e32 v36, v36, v44
	v_mul_f32_e32 v44, v36, v32
	v_mul_f32_e32 v32, 0xbfb8aa3b, v45
	v_mul_f32_e32 v36, 0xbfb8aa3b, v37
	v_exp_f32_e32 v32, v32
	v_exp_f32_e32 v36, v36
	v_add_f32_e32 v32, 1.0, v32
	v_add_f32_e32 v36, 1.0, v36
	v_rcp_f32_e32 v32, v32
	v_rcp_f32_e32 v36, v36
	v_mul_f32_e32 v32, v45, v32
	v_mul_f32_e32 v36, v37, v36
	v_mul_f32_e32 v32, v32, v41
	v_mul_f32_e32 v41, v36, v33
	v_mul_f32_e32 v36, 0xbfb8aa3b, v38
	v_exp_f32_e32 v36, v36
	v_mul_f32_e32 v33, 0xbfb8aa3b, v46
	v_exp_f32_e32 v33, v33
	v_cvt_pk_bf16_f32 v32, v40, v32
	v_add_f32_e32 v36, 1.0, v36
	v_rcp_f32_e32 v36, v36
	v_add_f32_e32 v33, 1.0, v33
; __device__ __forceinline__ float silu(float x) { return x * __builtin_amdgcn_rcpf(1.f + __expf(-x)); }
; __device__ __forceinline__ u32x4 pack8(const f32x4 a, const f32x4 b) { u32x4 w; w.x = cvt_pk_bf16(a[0], a[1]); w.y = cvt_pk_bf16(a[2], a[3]); w.z = cvt_pk_bf16(b[0], b[1]); w.w = cvt_pk_bf16(b[2], b[3]); return w; }
;     __device__ __forceinline__ void operator()(const f32x4 (&acc)[2][2][4][2], const Unit& u, int wr, int wc, int fr, int fq) const {
;         const int row0 = u.pm * BM + wr * 64 + fr; bf16_t* base = O + u.pn * 128 + wc * 32 + 8 * fq;
; #pragma unroll
;         for (int ai = 0; ai < 2; ++ai)
; #pragma unroll
;             for (int m = 0; m < 4; ++m) { bf16_t* rowp = base + (size_t)(row0 + ai * HALF + m * 16) * ldc; f32x4 v0, v1;
; #pragma unroll
;                 for (int j = 0; j < 4; ++j) { v0[j] = silu(acc[ai][0][m][0][j]) * acc[ai][1][m][0][j]; v1[j] = silu(acc[ai][0][m][1][j]) * acc[ai][1][m][1][j]; }
;                 *(u32x4*)rowp = pack8(v0, v1); }
;     }
	v_rcp_f32_e32 v33, v33
	v_mul_f32_e32 v36, v38, v36
	v_mul_f32_e32 v38, v36, v34
	v_mul_f32_e32 v34, 0xbfb8aa3b, v47
	v_mul_f32_e32 v36, 0xbfb8aa3b, v39
	v_exp_f32_e32 v34, v34
	v_exp_f32_e32 v36, v36
	v_mul_f32_e32 v33, v46, v33
	v_mul_f32_e32 v33, v33, v42
	v_add_f32_e32 v34, 1.0, v34
	v_add_f32_e32 v36, 1.0, v36
	v_rcp_f32_e32 v34, v34
	v_rcp_f32_e32 v36, v36
	v_mul_f32_e32 v34, v47, v34
	v_mul_f32_e32 v36, v39, v36
	v_mul_f32_e32 v34, v34, v43
	v_mul_f32_e32 v35, v36, v35
	v_mad_i64_i32 v[36:37], s[16:17], v48, s9, v[140:141]
	v_cvt_pk_bf16_f32 v33, v33, v34
	v_cvt_pk_bf16_f32 v34, v44, v41
	v_cvt_pk_bf16_f32 v35, v38, v35
	global_store_dwordx4 v[36:37], v[32:35], off nt
	s_nop 1
	v_mul_f32_e32 v33, 0xbfb8aa3b, v28
	v_exp_f32_e32 v33, v33
	v_add_u32_e32 v32, 0xa0, v146
	v_add_f32_e32 v33, 1.0, v33
	v_rcp_f32_e32 v33, v33
	s_nop 0
	v_mul_f32_e32 v28, v28, v33
	v_mul_f32_e32 v24, v28, v24
	v_mul_f32_e32 v28, 0xbfb8aa3b, v20
	v_exp_f32_e32 v28, v28
	s_nop 0
	v_add_f32_e32 v28, 1.0, v28
	v_rcp_f32_e32 v28, v28
	s_nop 0
	v_mul_f32_e32 v20, v20, v28
	v_mul_f32_e32 v28, v20, v16
	v_mul_f32_e32 v16, 0xbfb8aa3b, v29
	v_mul_f32_e32 v20, 0xbfb8aa3b, v21
	v_exp_f32_e32 v16, v16
	v_exp_f32_e32 v20, v20
	v_add_f32_e32 v16, 1.0, v16
	v_add_f32_e32 v20, 1.0, v20
	v_rcp_f32_e32 v16, v16
	v_rcp_f32_e32 v20, v20
	v_mul_f32_e32 v16, v29, v16
	v_mul_f32_e32 v20, v21, v20
	v_mul_f32_e32 v16, v16, v25
	v_mul_f32_e32 v25, v20, v17
	v_mul_f32_e32 v20, 0xbfb8aa3b, v22
	v_exp_f32_e32 v20, v20
	v_mul_f32_e32 v17, 0xbfb8aa3b, v30
	v_exp_f32_e32 v17, v17
	v_cvt_pk_bf16_f32 v16, v24, v16
	v_add_f32_e32 v20, 1.0, v20
	v_rcp_f32_e32 v20, v20
	v_add_f32_e32 v17, 1.0, v17
	v_rcp_f32_e32 v17, v17
	v_mul_f32_e32 v20, v22, v20
	v_mul_f32_e32 v22, v20, v18
	v_mul_f32_e32 v18, 0xbfb8aa3b, v31
	v_mul_f32_e32 v20, 0xbfb8aa3b, v23
	v_exp_f32_e32 v18, v18
	v_exp_f32_e32 v20, v20
	v_mul_f32_e32 v17, v30, v17
	v_mul_f32_e32 v17, v17, v26
	v_add_f32_e32 v18, 1.0, v18
	v_add_f32_e32 v20, 1.0, v20
	v_rcp_f32_e32 v18, v18
	v_rcp_f32_e32 v20, v20
	v_mul_f32_e32 v18, v31, v18
	v_mul_f32_e32 v20, v23, v20
	v_mul_f32_e32 v18, v18, v27
	v_mul_f32_e32 v19, v20, v19
	v_mad_i64_i32 v[20:21], s[16:17], v32, s9, v[140:141]
	v_cvt_pk_bf16_f32 v17, v17, v18
	v_cvt_pk_bf16_f32 v18, v28, v25
	v_cvt_pk_bf16_f32 v19, v22, v19
	global_store_dwordx4 v[20:21], v[16:19], off nt
	s_nop 1
	v_mul_f32_e32 v17, 0xbfb8aa3b, v12
	v_exp_f32_e32 v17, v17
	v_add_u32_e32 v16, 0xb0, v146
	v_add_f32_e32 v17, 1.0, v17
	v_rcp_f32_e32 v17, v17
	s_nop 0
	v_mul_f32_e32 v12, v12, v17
	v_mul_f32_e32 v8, v12, v8
	v_mul_f32_e32 v12, 0xbfb8aa3b, v4
	v_exp_f32_e32 v12, v12
	s_nop 0
	v_add_f32_e32 v12, 1.0, v12
	v_rcp_f32_e32 v12, v12
	s_nop 0
	v_mul_f32_e32 v4, v4, v12
	v_mul_f32_e32 v12, v4, v0
	v_mul_f32_e32 v0, 0xbfb8aa3b, v13
	v_mul_f32_e32 v4, 0xbfb8aa3b, v5
	v_exp_f32_e32 v0, v0
	v_exp_f32_e32 v4, v4
	v_add_f32_e32 v0, 1.0, v0
	v_add_f32_e32 v4, 1.0, v4
	v_rcp_f32_e32 v0, v0
	v_rcp_f32_e32 v4, v4
	v_mul_f32_e32 v0, v13, v0
	v_mul_f32_e32 v4, v5, v4
	v_mul_f32_e32 v0, v0, v9
	v_mul_f32_e32 v9, v4, v1
	v_mul_f32_e32 v4, 0xbfb8aa3b, v6
	v_exp_f32_e32 v4, v4
	v_mul_f32_e32 v1, 0xbfb8aa3b, v14
	v_exp_f32_e32 v1, v1
	v_cvt_pk_bf16_f32 v0, v8, v0
	v_add_f32_e32 v4, 1.0, v4
	v_rcp_f32_e32 v4, v4
	v_add_f32_e32 v1, 1.0, v1
	v_rcp_f32_e32 v1, v1
	v_mul_f32_e32 v4, v6, v4
	v_mul_f32_e32 v6, v4, v2
	v_mul_f32_e32 v4, 0xbfb8aa3b, v7
	v_mul_f32_e32 v2, 0xbfb8aa3b, v15
	v_exp_f32_e32 v4, v4
	v_exp_f32_e32 v2, v2
	v_mul_f32_e32 v1, v14, v1
	v_mul_f32_e32 v1, v1, v10
	v_add_f32_e32 v4, 1.0, v4
	v_add_f32_e32 v2, 1.0, v2
	v_rcp_f32_e32 v4, v4
	v_rcp_f32_e32 v2, v2
	v_mul_f32_e32 v4, v7, v4
	v_mul_f32_e32 v2, v15, v2
	v_mul_f32_e32 v3, v4, v3
	v_mad_i64_i32 v[4:5], s[16:17], v16, s9, v[140:141]
	v_mul_f32_e32 v2, v2, v11
	s_mov_b64 s[16:17], -1
	v_cvt_pk_bf16_f32 v1, v1, v2
	v_cvt_pk_bf16_f32 v2, v12, v9
	v_cvt_pk_bf16_f32 v3, v6, v3
	global_store_dwordx4 v[4:5], v[0:3], off nt
	s_cbranch_vccnz .LBB0_1114
	s_andn2_b64 vcc, exec, s[0:1]
	s_cbranch_vccnz .LBB0_1113
	s_barrier
	s_branch .LBB0_1113
